# G1 GLU epilogue hand-written (5 VALU/output, interleaved) + residual-norm epilogue xor16/32 shuffles as permlane swaps
# speedup vs baseline: 1.0040x; 1.0040x over previous
; __device__ __forceinline__ unsigned cvt_pk_bf16(float lo, float hi) { unsigned r; asm volatile("v_cvt_pk_bf16_f32 %0, %1, %2" : "=v"(r) : "v"(lo), "v"(hi)); return r; }
; __device__ __forceinline__ float sigmoid_f(float x) { return __builtin_amdgcn_rcpf(1.0f + __builtin_amdgcn_exp2f(-1.4426950408889634f * x)); }
;     __device__ __forceinline__ void operator()(const f32x4 (&acc)[2][2][4][2], const pg8::Unit& u, int wr, int wc, int fr, int fq, LAS unsigned char* lds, int wid, int lane, const pg8::Unit& nxt, bool has_next, int ui) const {
;     ...
;         if (u.pn < 4) {
;             const int col = u.pn * 128 + wc * 32 + fq * 8;
; #pragma unroll
;             for (int ai = 0; ai < 2; ++ai)
; #pragma unroll
;                 for (int m = 0; m < 4; ++m) {
;                     const int row = row0 + ai * 128 + m * 16; const float r_ = rs[ai][m];
;                     const f32x4 v0 = acc[ai][0][m][0] * r_, v1 = acc[ai][0][m][1] * r_, g0 = acc[ai][1][m][0] * r_, g1 = acc[ai][1][m][1] * r_;
;                     v4u w;
;                     w.x = cvt_pk_bf16(v0[0] * sigmoid_f(g0[0]), v0[1] * sigmoid_f(g0[1])); w.y = cvt_pk_bf16(v0[2] * sigmoid_f(g0[2]), v0[3] * sigmoid_f(g0[3]));
;                     w.z = cvt_pk_bf16(v1[0] * sigmoid_f(g1[0]), v1[1] * sigmoid_f(g1[1])); w.w = cvt_pk_bf16(v1[2] * sigmoid_f(g1[2]), v1[3] * sigmoid_f(g1[3]));
;                     *(v4u*)(CG + (size_t)row * CW + col) = w;
.LBB0_169:
	s_andn2_b64 vcc, exec, s[24:25]
	s_cbranch_vccnz .LBB0_171
	s_waitcnt lgkmcnt(0)
	v_readlane_b32 s24, v252, 39
	v_readlane_b32 s25, v252, 40
	v_lshl_or_b32 v230, s58, 7, v167
	v_ashrrev_i32_e32 v231, 31, v230
	v_lshlrev_b64 v[232:233], 1, v[230:231]
	s_nop 0
	v_lshl_add_u64 v[232:233], s[24:25], 0, v[232:233]
	v_mov_b32_e32 v235, 0
	v_mul_f32_e32 v240, 0xbfb8aa3b, v162
	v_rcp_f32_e32 v241, v162
	v_mul_f32_e32 v118, v240, v118
	v_mul_f32_e32 v119, v240, v119
	v_mul_f32_e32 v120, v240, v120
	v_mul_f32_e32 v121, v240, v121
	v_mul_f32_e32 v114, v240, v114
	v_mul_f32_e32 v115, v240, v115
	v_mul_f32_e32 v116, v240, v116
	v_mul_f32_e32 v117, v240, v117
	v_exp_f32_e32 v118, v118
	v_exp_f32_e32 v119, v119
	v_exp_f32_e32 v120, v120
	v_exp_f32_e32 v121, v121
	v_exp_f32_e32 v114, v114
	v_exp_f32_e32 v115, v115
	v_exp_f32_e32 v116, v116
	v_exp_f32_e32 v117, v117
	v_fma_f32 v118, v118, v241, v241
	v_fma_f32 v119, v119, v241, v241
	v_fma_f32 v120, v120, v241, v241
	v_fma_f32 v121, v121, v241, v241
	v_fma_f32 v114, v114, v241, v241
	v_fma_f32 v115, v115, v241, v241
	v_fma_f32 v116, v116, v241, v241
	v_fma_f32 v117, v117, v241, v241
	v_rcp_f32_e32 v118, v118
	v_rcp_f32_e32 v119, v119
	v_rcp_f32_e32 v120, v120
	v_rcp_f32_e32 v121, v121
	v_rcp_f32_e32 v114, v114
	v_rcp_f32_e32 v115, v115
	v_rcp_f32_e32 v116, v116
	v_rcp_f32_e32 v117, v117
	v_mul_f32_e32 v130, v130, v118
	v_mul_f32_e32 v131, v131, v119
	v_mul_f32_e32 v132, v132, v120
	v_mul_f32_e32 v133, v133, v121
	v_mul_f32_e32 v126, v126, v114
	v_mul_f32_e32 v127, v127, v115
	v_mul_f32_e32 v128, v128, v116
	v_mul_f32_e32 v129, v129, v117
	v_cvt_pk_bf16_f32 v130, v130, v131
	v_cvt_pk_bf16_f32 v131, v132, v133
	v_cvt_pk_bf16_f32 v132, v126, v127
	v_cvt_pk_bf16_f32 v133, v128, v129
	v_mov_b32_e32 v236, v160
	v_lshlrev_b32_e32 v234, 10, v236
	v_lshl_add_u64 v[238:239], v[232:233], 0, v[234:235]
	global_store_dwordx4 v[238:239], v[130:133], off
	v_mul_f32_e32 v240, 0xbfb8aa3b, v163
	v_rcp_f32_e32 v241, v163
	v_mul_f32_e32 v102, v240, v102
	v_mul_f32_e32 v103, v240, v103
	v_mul_f32_e32 v104, v240, v104
	v_mul_f32_e32 v105, v240, v105
	v_mul_f32_e32 v98, v240, v98
	v_mul_f32_e32 v99, v240, v99
	v_mul_f32_e32 v100, v240, v100
	v_mul_f32_e32 v101, v240, v101
	v_exp_f32_e32 v102, v102
	v_exp_f32_e32 v103, v103
	v_exp_f32_e32 v104, v104
	v_exp_f32_e32 v105, v105
	v_exp_f32_e32 v98, v98
	v_exp_f32_e32 v99, v99
	v_exp_f32_e32 v100, v100
	v_exp_f32_e32 v101, v101
	v_fma_f32 v102, v102, v241, v241
	v_fma_f32 v103, v103, v241, v241
	v_fma_f32 v104, v104, v241, v241
	v_fma_f32 v105, v105, v241, v241
	v_fma_f32 v98, v98, v241, v241
	v_fma_f32 v99, v99, v241, v241
	v_fma_f32 v100, v100, v241, v241
	v_fma_f32 v101, v101, v241, v241
	v_rcp_f32_e32 v102, v102
	v_rcp_f32_e32 v103, v103
	v_rcp_f32_e32 v104, v104
	v_rcp_f32_e32 v105, v105
	v_rcp_f32_e32 v98, v98
	v_rcp_f32_e32 v99, v99
	v_rcp_f32_e32 v100, v100
	v_rcp_f32_e32 v101, v101
	v_mul_f32_e32 v110, v110, v102
	v_mul_f32_e32 v111, v111, v103
	v_mul_f32_e32 v112, v112, v104
	v_mul_f32_e32 v113, v113, v105
	v_mul_f32_e32 v106, v106, v98
	v_mul_f32_e32 v107, v107, v99
	v_mul_f32_e32 v108, v108, v100
	v_mul_f32_e32 v109, v109, v101
	v_cvt_pk_bf16_f32 v110, v110, v111
	v_cvt_pk_bf16_f32 v111, v112, v113
	v_cvt_pk_bf16_f32 v112, v106, v107
	v_cvt_pk_bf16_f32 v113, v108, v109
	v_or_b32_e32 v236, 16, v160
	v_lshlrev_b32_e32 v234, 10, v236
	v_lshl_add_u64 v[238:239], v[232:233], 0, v[234:235]
	global_store_dwordx4 v[238:239], v[110:113], off
	v_mul_f32_e32 v240, 0xbfb8aa3b, v158
	v_rcp_f32_e32 v241, v158
	v_mul_f32_e32 v86, v240, v86
	v_mul_f32_e32 v87, v240, v87
	v_mul_f32_e32 v88, v240, v88
	v_mul_f32_e32 v89, v240, v89
	v_mul_f32_e32 v82, v240, v82
	v_mul_f32_e32 v83, v240, v83
	v_mul_f32_e32 v84, v240, v84
	v_mul_f32_e32 v85, v240, v85
	v_exp_f32_e32 v86, v86
	v_exp_f32_e32 v87, v87
	v_exp_f32_e32 v88, v88
	v_exp_f32_e32 v89, v89
	v_exp_f32_e32 v82, v82
	v_exp_f32_e32 v83, v83
	v_exp_f32_e32 v84, v84
	v_exp_f32_e32 v85, v85
	v_fma_f32 v86, v86, v241, v241
	v_fma_f32 v87, v87, v241, v241
	v_fma_f32 v88, v88, v241, v241
	v_fma_f32 v89, v89, v241, v241
	v_fma_f32 v82, v82, v241, v241
	v_fma_f32 v83, v83, v241, v241
	v_fma_f32 v84, v84, v241, v241
	v_fma_f32 v85, v85, v241, v241
	v_rcp_f32_e32 v86, v86
	v_rcp_f32_e32 v87, v87
	v_rcp_f32_e32 v88, v88
	v_rcp_f32_e32 v89, v89
	v_rcp_f32_e32 v82, v82
	v_rcp_f32_e32 v83, v83
	v_rcp_f32_e32 v84, v84
	v_rcp_f32_e32 v85, v85
	v_mul_f32_e32 v94, v94, v86
	v_mul_f32_e32 v95, v95, v87
	v_mul_f32_e32 v96, v96, v88
	v_mul_f32_e32 v97, v97, v89
	v_mul_f32_e32 v90, v90, v82
	v_mul_f32_e32 v91, v91, v83
	v_mul_f32_e32 v92, v92, v84
	v_mul_f32_e32 v93, v93, v85
	v_cvt_pk_bf16_f32 v94, v94, v95
	v_cvt_pk_bf16_f32 v95, v96, v97
	v_cvt_pk_bf16_f32 v96, v90, v91
	v_cvt_pk_bf16_f32 v97, v92, v93
	v_or_b32_e32 v236, 32, v160
	v_lshlrev_b32_e32 v234, 10, v236
	v_lshl_add_u64 v[238:239], v[232:233], 0, v[234:235]
	global_store_dwordx4 v[238:239], v[94:97], off
	v_mul_f32_e32 v240, 0xbfb8aa3b, v159
	v_rcp_f32_e32 v241, v159
	v_mul_f32_e32 v70, v240, v70
	v_mul_f32_e32 v71, v240, v71
	v_mul_f32_e32 v72, v240, v72
	v_mul_f32_e32 v73, v240, v73
	v_mul_f32_e32 v66, v240, v66
	v_mul_f32_e32 v67, v240, v67
	v_mul_f32_e32 v68, v240, v68
	v_mul_f32_e32 v69, v240, v69
	v_exp_f32_e32 v70, v70
	v_exp_f32_e32 v71, v71
	v_exp_f32_e32 v72, v72
	v_exp_f32_e32 v73, v73
	v_exp_f32_e32 v66, v66
	v_exp_f32_e32 v67, v67
	v_exp_f32_e32 v68, v68
	v_exp_f32_e32 v69, v69
	v_fma_f32 v70, v70, v241, v241
	v_fma_f32 v71, v71, v241, v241
	v_fma_f32 v72, v72, v241, v241
	v_fma_f32 v73, v73, v241, v241
	v_fma_f32 v66, v66, v241, v241
	v_fma_f32 v67, v67, v241, v241
; __device__ __forceinline__ unsigned cvt_pk_bf16(float lo, float hi) { unsigned r; asm volatile("v_cvt_pk_bf16_f32 %0, %1, %2" : "=v"(r) : "v"(lo), "v"(hi)); return r; }
; __device__ __forceinline__ float sigmoid_f(float x) { return __builtin_amdgcn_rcpf(1.0f + __builtin_amdgcn_exp2f(-1.4426950408889634f * x)); }
;     __device__ __forceinline__ void operator()(const f32x4 (&acc)[2][2][4][2], const pg8::Unit& u, int wr, int wc, int fr, int fq, LAS unsigned char* lds, int wid, int lane, const pg8::Unit& nxt, bool has_next, int ui) const {
;     ...
;             for (int ai = 0; ai < 2; ++ai)
; #pragma unroll
;                 for (int m = 0; m < 4; ++m) {
;                     const int row = row0 + ai * 128 + m * 16; const float r_ = rs[ai][m];
;                     const f32x4 v0 = acc[ai][0][m][0] * r_, v1 = acc[ai][0][m][1] * r_, g0 = acc[ai][1][m][0] * r_, g1 = acc[ai][1][m][1] * r_;
;                     v4u w;
;                     w.x = cvt_pk_bf16(v0[0] * sigmoid_f(g0[0]), v0[1] * sigmoid_f(g0[1])); w.y = cvt_pk_bf16(v0[2] * sigmoid_f(g0[2]), v0[3] * sigmoid_f(g0[3]));
;                     w.z = cvt_pk_bf16(v1[0] * sigmoid_f(g1[0]), v1[1] * sigmoid_f(g1[1])); w.w = cvt_pk_bf16(v1[2] * sigmoid_f(g1[2]), v1[3] * sigmoid_f(g1[3]));
;                     *(v4u*)(CG + (size_t)row * CW + col) = w;
	v_fma_f32 v68, v68, v241, v241
	v_fma_f32 v69, v69, v241, v241
	v_rcp_f32_e32 v70, v70
	v_rcp_f32_e32 v71, v71
	v_rcp_f32_e32 v72, v72
	v_rcp_f32_e32 v73, v73
	v_rcp_f32_e32 v66, v66
	v_rcp_f32_e32 v67, v67
	v_rcp_f32_e32 v68, v68
	v_rcp_f32_e32 v69, v69
	v_mul_f32_e32 v78, v78, v70
	v_mul_f32_e32 v79, v79, v71
	v_mul_f32_e32 v80, v80, v72
	v_mul_f32_e32 v81, v81, v73
	v_mul_f32_e32 v74, v74, v66
	v_mul_f32_e32 v75, v75, v67
	v_mul_f32_e32 v76, v76, v68
	v_mul_f32_e32 v77, v77, v69
	v_cvt_pk_bf16_f32 v78, v78, v79
	v_cvt_pk_bf16_f32 v79, v80, v81
	v_cvt_pk_bf16_f32 v80, v74, v75
	v_cvt_pk_bf16_f32 v81, v76, v77
	v_or_b32_e32 v236, 48, v160
	v_lshlrev_b32_e32 v234, 10, v236
	v_lshl_add_u64 v[238:239], v[232:233], 0, v[234:235]
	global_store_dwordx4 v[238:239], v[78:81], off
	v_mul_f32_e32 v240, 0xbfb8aa3b, v154
	v_rcp_f32_e32 v241, v154
	v_mul_f32_e32 v54, v240, v54
	v_mul_f32_e32 v55, v240, v55
	v_mul_f32_e32 v56, v240, v56
	v_mul_f32_e32 v57, v240, v57
	v_mul_f32_e32 v50, v240, v50
	v_mul_f32_e32 v51, v240, v51
	v_mul_f32_e32 v52, v240, v52
	v_mul_f32_e32 v53, v240, v53
	v_exp_f32_e32 v54, v54
	v_exp_f32_e32 v55, v55
	v_exp_f32_e32 v56, v56
	v_exp_f32_e32 v57, v57
	v_exp_f32_e32 v50, v50
	v_exp_f32_e32 v51, v51
	v_exp_f32_e32 v52, v52
	v_exp_f32_e32 v53, v53
	v_fma_f32 v54, v54, v241, v241
	v_fma_f32 v55, v55, v241, v241
	v_fma_f32 v56, v56, v241, v241
	v_fma_f32 v57, v57, v241, v241
	v_fma_f32 v50, v50, v241, v241
	v_fma_f32 v51, v51, v241, v241
	v_fma_f32 v52, v52, v241, v241
	v_fma_f32 v53, v53, v241, v241
	v_rcp_f32_e32 v54, v54
	v_rcp_f32_e32 v55, v55
	v_rcp_f32_e32 v56, v56
	v_rcp_f32_e32 v57, v57
	v_rcp_f32_e32 v50, v50
	v_rcp_f32_e32 v51, v51
	v_rcp_f32_e32 v52, v52
	v_rcp_f32_e32 v53, v53
	v_mul_f32_e32 v62, v62, v54
	v_mul_f32_e32 v63, v63, v55
	v_mul_f32_e32 v64, v64, v56
	v_mul_f32_e32 v65, v65, v57
	v_mul_f32_e32 v58, v58, v50
	v_mul_f32_e32 v59, v59, v51
	v_mul_f32_e32 v60, v60, v52
	v_mul_f32_e32 v61, v61, v53
	v_cvt_pk_bf16_f32 v62, v62, v63
	v_cvt_pk_bf16_f32 v63, v64, v65
	v_cvt_pk_bf16_f32 v64, v58, v59
	v_cvt_pk_bf16_f32 v65, v60, v61
	v_or_b32_e32 v236, 0x80, v160
	v_lshlrev_b32_e32 v234, 10, v236
	v_lshl_add_u64 v[238:239], v[232:233], 0, v[234:235]
	global_store_dwordx4 v[238:239], v[62:65], off
	v_mul_f32_e32 v240, 0xbfb8aa3b, v155
	v_rcp_f32_e32 v241, v155
	v_mul_f32_e32 v38, v240, v38
	v_mul_f32_e32 v39, v240, v39
	v_mul_f32_e32 v40, v240, v40
	v_mul_f32_e32 v41, v240, v41
	v_mul_f32_e32 v34, v240, v34
	v_mul_f32_e32 v35, v240, v35
	v_mul_f32_e32 v36, v240, v36
	v_mul_f32_e32 v37, v240, v37
	v_exp_f32_e32 v38, v38
	v_exp_f32_e32 v39, v39
	v_exp_f32_e32 v40, v40
	v_exp_f32_e32 v41, v41
	v_exp_f32_e32 v34, v34
	v_exp_f32_e32 v35, v35
	v_exp_f32_e32 v36, v36
	v_exp_f32_e32 v37, v37
	v_fma_f32 v38, v38, v241, v241
	v_fma_f32 v39, v39, v241, v241
	v_fma_f32 v40, v40, v241, v241
	v_fma_f32 v41, v41, v241, v241
	v_fma_f32 v34, v34, v241, v241
	v_fma_f32 v35, v35, v241, v241
	v_fma_f32 v36, v36, v241, v241
	v_fma_f32 v37, v37, v241, v241
	v_rcp_f32_e32 v38, v38
	v_rcp_f32_e32 v39, v39
	v_rcp_f32_e32 v40, v40
	v_rcp_f32_e32 v41, v41
	v_rcp_f32_e32 v34, v34
	v_rcp_f32_e32 v35, v35
	v_rcp_f32_e32 v36, v36
	v_rcp_f32_e32 v37, v37
	v_mul_f32_e32 v46, v46, v38
	v_mul_f32_e32 v47, v47, v39
	v_mul_f32_e32 v48, v48, v40
	v_mul_f32_e32 v49, v49, v41
	v_mul_f32_e32 v42, v42, v34
	v_mul_f32_e32 v43, v43, v35
	v_mul_f32_e32 v44, v44, v36
	v_mul_f32_e32 v45, v45, v37
	v_cvt_pk_bf16_f32 v46, v46, v47
	v_cvt_pk_bf16_f32 v47, v48, v49
	v_cvt_pk_bf16_f32 v48, v42, v43
	v_cvt_pk_bf16_f32 v49, v44, v45
	v_or_b32_e32 v236, 0x90, v160
	v_lshlrev_b32_e32 v234, 10, v236
	v_lshl_add_u64 v[238:239], v[232:233], 0, v[234:235]
	global_store_dwordx4 v[238:239], v[46:49], off
	v_mul_f32_e32 v240, 0xbfb8aa3b, v152
	v_rcp_f32_e32 v241, v152
	v_mul_f32_e32 v22, v240, v22
	v_mul_f32_e32 v23, v240, v23
	v_mul_f32_e32 v24, v240, v24
	v_mul_f32_e32 v25, v240, v25
	v_mul_f32_e32 v18, v240, v18
	v_mul_f32_e32 v19, v240, v19
	v_mul_f32_e32 v20, v240, v20
	v_mul_f32_e32 v21, v240, v21
	v_exp_f32_e32 v22, v22
	v_exp_f32_e32 v23, v23
	v_exp_f32_e32 v24, v24
	v_exp_f32_e32 v25, v25
	v_exp_f32_e32 v18, v18
	v_exp_f32_e32 v19, v19
	v_exp_f32_e32 v20, v20
	v_exp_f32_e32 v21, v21
	v_fma_f32 v22, v22, v241, v241
	v_fma_f32 v23, v23, v241, v241
	v_fma_f32 v24, v24, v241, v241
	v_fma_f32 v25, v25, v241, v241
	v_fma_f32 v18, v18, v241, v241
	v_fma_f32 v19, v19, v241, v241
	v_fma_f32 v20, v20, v241, v241
	v_fma_f32 v21, v21, v241, v241
	v_rcp_f32_e32 v22, v22
	v_rcp_f32_e32 v23, v23
	v_rcp_f32_e32 v24, v24
	v_rcp_f32_e32 v25, v25
	v_rcp_f32_e32 v18, v18
	v_rcp_f32_e32 v19, v19
	v_rcp_f32_e32 v20, v20
	v_rcp_f32_e32 v21, v21
	v_mul_f32_e32 v30, v30, v22
	v_mul_f32_e32 v31, v31, v23
	v_mul_f32_e32 v32, v32, v24
	v_mul_f32_e32 v33, v33, v25
	v_mul_f32_e32 v26, v26, v18
	v_mul_f32_e32 v27, v27, v19
	v_mul_f32_e32 v28, v28, v20
	v_mul_f32_e32 v29, v29, v21
	v_cvt_pk_bf16_f32 v30, v30, v31
	v_cvt_pk_bf16_f32 v31, v32, v33
	v_cvt_pk_bf16_f32 v32, v26, v27
	v_cvt_pk_bf16_f32 v33, v28, v29
	v_or_b32_e32 v236, 0xa0, v160
	v_lshlrev_b32_e32 v234, 10, v236
	v_lshl_add_u64 v[238:239], v[232:233], 0, v[234:235]
	global_store_dwordx4 v[238:239], v[30:33], off
	v_mul_f32_e32 v240, 0xbfb8aa3b, v153
	v_rcp_f32_e32 v241, v153
	v_mul_f32_e32 v6, v240, v6
	v_mul_f32_e32 v7, v240, v7
	v_mul_f32_e32 v8, v240, v8
	v_mul_f32_e32 v9, v240, v9
	v_mul_f32_e32 v2, v240, v2
	v_mul_f32_e32 v3, v240, v3
	v_mul_f32_e32 v4, v240, v4
	v_mul_f32_e32 v5, v240, v5
	v_exp_f32_e32 v6, v6
	v_exp_f32_e32 v7, v7
	v_exp_f32_e32 v8, v8
	v_exp_f32_e32 v9, v9
	v_exp_f32_e32 v2, v2
	v_exp_f32_e32 v3, v3
	v_exp_f32_e32 v4, v4
	v_exp_f32_e32 v5, v5
	v_fma_f32 v6, v6, v241, v241
	v_fma_f32 v7, v7, v241, v241
	v_fma_f32 v8, v8, v241, v241
	v_fma_f32 v9, v9, v241, v241
	v_fma_f32 v2, v2, v241, v241
	v_fma_f32 v3, v3, v241, v241
	v_fma_f32 v4, v4, v241, v241
	v_fma_f32 v5, v5, v241, v241
	v_rcp_f32_e32 v6, v6
	v_rcp_f32_e32 v7, v7
	v_rcp_f32_e32 v8, v8
	v_rcp_f32_e32 v9, v9
	v_rcp_f32_e32 v2, v2
	v_rcp_f32_e32 v3, v3
	v_rcp_f32_e32 v4, v4
	v_rcp_f32_e32 v5, v5
	v_mul_f32_e32 v14, v14, v6
	v_mul_f32_e32 v15, v15, v7
	v_mul_f32_e32 v16, v16, v8
	v_mul_f32_e32 v17, v17, v9
	v_mul_f32_e32 v10, v10, v2
	v_mul_f32_e32 v11, v11, v3
	v_mul_f32_e32 v12, v12, v4
	v_mul_f32_e32 v13, v13, v5
	v_cvt_pk_bf16_f32 v14, v14, v15
	v_cvt_pk_bf16_f32 v15, v16, v17
	v_cvt_pk_bf16_f32 v16, v10, v11
	v_cvt_pk_bf16_f32 v17, v12, v13
	v_or_b32_e32 v236, 0xb0, v160
	v_lshlrev_b32_e32 v234, 10, v236
	v_lshl_add_u64 v[238:239], v[232:233], 0, v[234:235]
	global_store_dwordx4 v[238:239], v[14:17], off

;     __device__ __forceinline__ void operator()(const f32x4 (&acc)[2][2][4][2], const pg8::Unit& u, int wr, int wc, int fr, int fq, LAS unsigned char* lds, int wid, int lane, const pg8::Unit& nxt, bool has_next, int ui) const {
;     ...
;         v4u xv[4][2];
; #pragma unroll
;         for (int m = 0; m < 4; ++m)
; #pragma unroll
;             for (int bj = 0; bj < 2; ++bj) xv[m][bj] = *(const v4u*)(X + (rowbase + rl0 + m * 16) * DM + col0 + bj * 128);
;         f32x4 gv[2][2];
; #pragma unroll
;         for (int bj = 0; bj < 2; ++bj)
; #pragma unroll
;             for (int n = 0; n < 2; ++n) gv[bj][n] = *(const f32x4*)(gpost + col0 + bj * 128 + 4 * n);
; #pragma unroll
;         for (int ai = 0; ai < 2; ++ai)
; #pragma unroll
;             for (int m = 0; m < 4; ++m) { float ss = 0.f;
; #pragma unroll
;                 for (int bj = 0; bj < 2; ++bj)
; #pragma unroll
;                     for (int n = 0; n < 2; ++n) { const f32x4 v = acc[ai][bj][m][n]; ss += (v[0] * v[0] + v[1] * v[1]) + (v[2] * v[2] + v[3] * v[3]); }
;                 ss += __shfl_xor(ss, 16); ss += __shfl_xor(ss, 32);
;                 if (fq == 0) P[(rl0 + ai * 128 + m * 16) * 4 + wc] = ss; }
.LBB0_467:
	s_ashr_i32 s11, s10, 31
	v_lshl_or_b32 v208, s20, 8, v228
	s_lshl_b64 s[30:31], s[10:11], 8
	v_lshl_add_u64 v[90:91], s[30:31], 0, v[186:187]
	v_ashrrev_i32_e32 v209, 31, v208
	v_lshl_add_u64 v[92:93], v[208:209], 1, s[36:37]
	v_lshlrev_b64 v[216:217], 11, v[90:91]
	v_lshl_add_u64 v[90:91], v[92:93], 0, v[216:217]
	v_add_co_u32_e32 v92, vcc, 0x8000, v90
	s_mov_b32 s10, 0x10000
	s_nop 0
	v_addc_co_u32_e32 v93, vcc, 0, v91, vcc
	global_load_dwordx4 v[174:177], v[90:91], off
	global_load_dwordx4 v[170:173], v[90:91], off offset:256
	global_load_dwordx4 v[166:169], v[92:93], off
	global_load_dwordx4 v[162:165], v[92:93], off offset:256
	v_add_co_u32_e32 v92, vcc, s10, v90
	s_mov_b32 s10, 0x18000
	s_nop 0
	v_addc_co_u32_e32 v93, vcc, 0, v91, vcc
	v_add_co_u32_e32 v90, vcc, s10, v90
	v_lshl_add_u64 v[94:95], v[208:209], 2, s[16:17]
	s_nop 0
	v_addc_co_u32_e32 v91, vcc, 0, v91, vcc
	global_load_dwordx4 v[158:161], v[92:93], off
	global_load_dwordx4 v[154:157], v[92:93], off offset:256
	global_load_dwordx4 v[150:153], v[90:91], off
	global_load_dwordx4 v[146:149], v[90:91], off offset:256
	global_load_dwordx4 v[98:101], v[94:95], off offset:16
	global_load_dwordx4 v[106:109], v[94:95], off
	s_nop 0
	global_load_dwordx4 v[90:93], v[94:95], off offset:528
	s_nop 0
	global_load_dwordx4 v[94:97], v[94:95], off offset:512
	v_and_b32_e32 v211, 64, v249
	v_xor_b32_e32 v210, 16, v249
	v_add_u32_e32 v211, 64, v211
	v_cmp_lt_i32_e32 vcc, v210, v211
	v_mul_f32_e32 v212, v145, v145
	v_fmac_f32_e32 v212, v144, v144
	v_cndmask_b32_e32 v210, v249, v210, vcc
	v_lshlrev_b32_e32 v241, 2, v210
	v_mul_f32_e32 v210, v143, v143
	v_fmac_f32_e32 v210, v142, v142
	v_add_f32_e32 v210, v210, v212
	v_mul_f32_e32 v212, v139, v139
	v_mul_f32_e32 v213, v141, v141
	v_fmac_f32_e32 v212, v138, v138
	v_fmac_f32_e32 v213, v140, v140
	v_add_f32_e32 v212, v212, v213
	v_add_f32_e32 v210, v210, v212
	v_mul_f32_e32 v212, v135, v135
	v_mul_f32_e32 v213, v137, v137
	v_fmac_f32_e32 v212, v134, v134
	v_fmac_f32_e32 v213, v136, v136
	v_add_f32_e32 v212, v212, v213
	v_add_f32_e32 v210, v210, v212
	v_mul_f32_e32 v212, v131, v131
	v_mul_f32_e32 v213, v133, v133
	v_fmac_f32_e32 v212, v130, v130
	v_fmac_f32_e32 v213, v132, v132
	v_add_f32_e32 v212, v212, v213
	v_add_f32_e32 v210, v210, v212
	v_mov_b32_e32 v212, v210
	s_nop 1
	v_permlane16_swap_b32_e32 v212, v210
	v_xor_b32_e32 v213, 32, v249
	v_cmp_lt_i32_e32 vcc, v213, v211
	s_waitcnt lgkmcnt(0)
	v_add_f32_e32 v214, v210, v212
	v_cndmask_b32_e32 v211, v249, v213, vcc
	v_lshlrev_b32_e32 v242, 2, v211
	v_mov_b32_e32 v215, v214
	s_nop 1
	v_permlane32_swap_b32_e32 v215, v214
	s_and_saveexec_b64 s[10:11], s[0:1]
	s_cbranch_execz .LBB0_469
	s_waitcnt lgkmcnt(0)
	v_add_f32_e32 v210, v214, v215
	ds_write_b32 v230, v210
.LBB0_469:
	s_or_b64 exec, exec, s[10:11]
	v_mul_f32_e32 v210, v127, v127
	v_mul_f32_e32 v211, v129, v129
	v_fmac_f32_e32 v210, v126, v126
	v_fmac_f32_e32 v211, v128, v128
	v_add_f32_e32 v210, v210, v211
	v_mul_f32_e32 v211, v123, v123
	v_mul_f32_e32 v212, v125, v125
	v_fmac_f32_e32 v211, v122, v122
	v_fmac_f32_e32 v212, v124, v124
	v_add_f32_e32 v211, v211, v212
	v_add_f32_e32 v210, v210, v211
	v_mul_f32_e32 v211, v119, v119
	v_mul_f32_e32 v212, v121, v121
	v_fmac_f32_e32 v211, v118, v118
	v_fmac_f32_e32 v212, v120, v120
	v_add_f32_e32 v211, v211, v212
	v_add_f32_e32 v210, v210, v211
	v_mul_f32_e32 v211, v115, v115
	v_mul_f32_e32 v212, v117, v117
	v_fmac_f32_e32 v211, v114, v114
	v_fmac_f32_e32 v212, v116, v116
	v_add_f32_e32 v211, v211, v212
	v_add_f32_e32 v210, v210, v211
	v_mov_b32_e32 v211, v210
	s_nop 1
	v_permlane16_swap_b32_e32 v211, v210
	s_waitcnt lgkmcnt(0)
	v_add_f32_e32 v214, v210, v211
	v_mov_b32_e32 v215, v214
	s_nop 1
	v_permlane32_swap_b32_e32 v215, v214
	s_and_saveexec_b64 s[10:11], s[0:1]
	s_cbranch_execz .LBB0_471
	s_waitcnt lgkmcnt(0)
	v_add_f32_e32 v210, v214, v215
	ds_write_b32 v230, v210 offset:256
.LBB0_471:
	s_or_b64 exec, exec, s[10:11]
	v_mul_f32_e32 v210, v111, v111
	v_mul_f32_e32 v211, v113, v113
	v_fmac_f32_e32 v210, v110, v110
	v_fmac_f32_e32 v211, v112, v112
	v_add_f32_e32 v210, v210, v211
	v_mul_f32_e32 v211, v103, v103
	v_mul_f32_e32 v212, v105, v105
	v_fmac_f32_e32 v211, v102, v102
	v_fmac_f32_e32 v212, v104, v104
	v_add_f32_e32 v211, v211, v212
	v_add_f32_e32 v210, v210, v211
	v_mul_f32_e32 v211, v87, v87
	v_mul_f32_e32 v212, v89, v89
	v_fmac_f32_e32 v211, v86, v86
	v_fmac_f32_e32 v212, v88, v88
	v_add_f32_e32 v211, v211, v212
	v_add_f32_e32 v210, v210, v211
	v_mul_f32_e32 v211, v83, v83
	v_mul_f32_e32 v212, v85, v85
	v_fmac_f32_e32 v211, v82, v82
	v_fmac_f32_e32 v212, v84, v84
	v_add_f32_e32 v211, v211, v212
	v_add_f32_e32 v210, v210, v211
	v_mov_b32_e32 v211, v210
	s_nop 1
	v_permlane16_swap_b32_e32 v211, v210
	s_waitcnt lgkmcnt(0)
	v_add_f32_e32 v214, v210, v211
	v_mov_b32_e32 v215, v214
	s_nop 1
	v_permlane32_swap_b32_e32 v215, v214
	s_and_saveexec_b64 s[10:11], s[0:1]
	s_cbranch_execz .LBB0_473
	s_waitcnt lgkmcnt(0)
	v_add_f32_e32 v210, v214, v215
	ds_write_b32 v230, v210 offset:512
;     __device__ __forceinline__ void operator()(const f32x4 (&acc)[2][2][4][2], const pg8::Unit& u, int wr, int wc, int fr, int fq, LAS unsigned char* lds, int wid, int lane, const pg8::Unit& nxt, bool has_next, int ui) const {
;     ...
;         for (int ai = 0; ai < 2; ++ai)
; #pragma unroll
;             for (int m = 0; m < 4; ++m) { float ss = 0.f;
; #pragma unroll
;                 for (int bj = 0; bj < 2; ++bj)
; #pragma unroll
;                     for (int n = 0; n < 2; ++n) { const f32x4 v = acc[ai][bj][m][n]; ss += (v[0] * v[0] + v[1] * v[1]) + (v[2] * v[2] + v[3] * v[3]); }
;                 ss += __shfl_xor(ss, 16); ss += __shfl_xor(ss, 32);
;                 if (fq == 0) P[(rl0 + ai * 128 + m * 16) * 4 + wc] = ss; }
.LBB0_473:
	s_or_b64 exec, exec, s[10:11]
	v_mul_f32_e32 v210, v79, v79
	v_mul_f32_e32 v211, v81, v81
	v_fmac_f32_e32 v210, v78, v78
	v_fmac_f32_e32 v211, v80, v80
	v_add_f32_e32 v210, v210, v211
	v_mul_f32_e32 v211, v75, v75
	v_mul_f32_e32 v212, v77, v77
	v_fmac_f32_e32 v211, v74, v74
	v_fmac_f32_e32 v212, v76, v76
	v_add_f32_e32 v211, v211, v212
	v_add_f32_e32 v210, v210, v211
	v_mul_f32_e32 v211, v71, v71
	v_mul_f32_e32 v212, v73, v73
	v_fmac_f32_e32 v211, v70, v70
	v_fmac_f32_e32 v212, v72, v72
	v_add_f32_e32 v211, v211, v212
	v_add_f32_e32 v210, v210, v211
	v_mul_f32_e32 v211, v67, v67
	v_mul_f32_e32 v212, v69, v69
	v_fmac_f32_e32 v211, v66, v66
	v_fmac_f32_e32 v212, v68, v68
	v_add_f32_e32 v211, v211, v212
	v_add_f32_e32 v210, v210, v211
	v_mov_b32_e32 v211, v210
	s_nop 1
	v_permlane16_swap_b32_e32 v211, v210
	s_waitcnt lgkmcnt(0)
	v_add_f32_e32 v214, v210, v211
	v_mov_b32_e32 v215, v214
	s_nop 1
	v_permlane32_swap_b32_e32 v215, v214
	s_and_saveexec_b64 s[10:11], s[0:1]
	s_cbranch_execz .LBB0_475
	s_waitcnt lgkmcnt(0)
	v_add_f32_e32 v210, v214, v215
	ds_write_b32 v230, v210 offset:768
.LBB0_475:
	s_or_b64 exec, exec, s[10:11]
	v_mul_f32_e32 v210, v63, v63
	v_mul_f32_e32 v211, v65, v65
	v_fmac_f32_e32 v210, v62, v62
	v_fmac_f32_e32 v211, v64, v64
	v_add_f32_e32 v210, v210, v211
	v_mul_f32_e32 v211, v59, v59
	v_mul_f32_e32 v212, v61, v61
	v_fmac_f32_e32 v211, v58, v58
	v_fmac_f32_e32 v212, v60, v60
	v_add_f32_e32 v211, v211, v212
	v_add_f32_e32 v210, v210, v211
	v_mul_f32_e32 v211, v55, v55
	v_mul_f32_e32 v212, v57, v57
	v_fmac_f32_e32 v211, v54, v54
	v_fmac_f32_e32 v212, v56, v56
	v_add_f32_e32 v211, v211, v212
	v_add_f32_e32 v210, v210, v211
	v_mul_f32_e32 v211, v51, v51
	v_mul_f32_e32 v212, v53, v53
	v_fmac_f32_e32 v211, v50, v50
	v_fmac_f32_e32 v212, v52, v52
	v_add_f32_e32 v211, v211, v212
	v_add_f32_e32 v210, v210, v211
	v_mov_b32_e32 v211, v210
	s_nop 1
	v_permlane16_swap_b32_e32 v211, v210
	s_waitcnt lgkmcnt(0)
	v_add_f32_e32 v214, v210, v211
	v_mov_b32_e32 v215, v214
	s_nop 1
	v_permlane32_swap_b32_e32 v215, v214
	s_and_saveexec_b64 s[10:11], s[0:1]
	s_cbranch_execz .LBB0_477
	s_waitcnt lgkmcnt(0)
	v_add_f32_e32 v210, v214, v215
	ds_write_b32 v230, v210 offset:2048
.LBB0_477:
	s_or_b64 exec, exec, s[10:11]
	v_mul_f32_e32 v210, v47, v47
	v_mul_f32_e32 v211, v49, v49
	v_fmac_f32_e32 v210, v46, v46
	v_fmac_f32_e32 v211, v48, v48
	v_add_f32_e32 v210, v210, v211
	v_mul_f32_e32 v211, v43, v43
	v_mul_f32_e32 v212, v45, v45
	v_fmac_f32_e32 v211, v42, v42
	v_fmac_f32_e32 v212, v44, v44
	v_add_f32_e32 v211, v211, v212
	v_add_f32_e32 v210, v210, v211
	v_mul_f32_e32 v211, v39, v39
	v_mul_f32_e32 v212, v41, v41
	v_fmac_f32_e32 v211, v38, v38
	v_fmac_f32_e32 v212, v40, v40
	v_add_f32_e32 v211, v211, v212
	v_add_f32_e32 v210, v210, v211
	v_mul_f32_e32 v211, v35, v35
	v_mul_f32_e32 v212, v37, v37
	v_fmac_f32_e32 v211, v34, v34
	v_fmac_f32_e32 v212, v36, v36
	v_add_f32_e32 v211, v211, v212
	v_add_f32_e32 v210, v210, v211
	v_mov_b32_e32 v211, v210
	s_nop 1
	v_permlane16_swap_b32_e32 v211, v210
	s_waitcnt lgkmcnt(0)
	v_add_f32_e32 v214, v210, v211
	v_mov_b32_e32 v215, v214
	s_nop 1
	v_permlane32_swap_b32_e32 v215, v214
	s_and_saveexec_b64 s[10:11], s[0:1]
	s_cbranch_execz .LBB0_479
	s_waitcnt lgkmcnt(0)
	v_add_f32_e32 v210, v214, v215
	ds_write_b32 v230, v210 offset:2304
.LBB0_479:
	s_or_b64 exec, exec, s[10:11]
	v_mul_f32_e32 v210, v31, v31
	v_mul_f32_e32 v211, v33, v33
	v_fmac_f32_e32 v210, v30, v30
	v_fmac_f32_e32 v211, v32, v32
	v_add_f32_e32 v210, v210, v211
	v_mul_f32_e32 v211, v27, v27
	v_mul_f32_e32 v212, v29, v29
	v_fmac_f32_e32 v211, v26, v26
	v_fmac_f32_e32 v212, v28, v28
	v_add_f32_e32 v211, v211, v212
	v_add_f32_e32 v210, v210, v211
	v_mul_f32_e32 v211, v23, v23
	v_mul_f32_e32 v212, v25, v25
	v_fmac_f32_e32 v211, v22, v22
	v_fmac_f32_e32 v212, v24, v24
	v_add_f32_e32 v211, v211, v212
	v_add_f32_e32 v210, v210, v211
	v_mul_f32_e32 v211, v19, v19
	v_mul_f32_e32 v212, v21, v21
	v_fmac_f32_e32 v211, v18, v18
	v_fmac_f32_e32 v212, v20, v20
	v_add_f32_e32 v211, v211, v212
	v_add_f32_e32 v210, v210, v211
	v_mov_b32_e32 v211, v210
	s_nop 1
	v_permlane16_swap_b32_e32 v211, v210
	s_waitcnt lgkmcnt(0)
	v_add_f32_e32 v214, v210, v211
	v_mov_b32_e32 v215, v214
	s_nop 1
	v_permlane32_swap_b32_e32 v215, v214
	s_and_saveexec_b64 s[10:11], s[0:1]
	s_cbranch_execz .LBB0_481
	s_waitcnt lgkmcnt(0)
	v_add_f32_e32 v210, v214, v215
	ds_write_b32 v230, v210 offset:2560
.LBB0_481:
	s_or_b64 exec, exec, s[10:11]
	v_mul_f32_e32 v210, v15, v15
	v_mul_f32_e32 v211, v17, v17
	v_fmac_f32_e32 v210, v14, v14
	v_fmac_f32_e32 v211, v16, v16
	v_add_f32_e32 v210, v210, v211
	v_mul_f32_e32 v211, v11, v11
	v_mul_f32_e32 v212, v13, v13
	v_fmac_f32_e32 v211, v10, v10
	v_fmac_f32_e32 v212, v12, v12
	v_add_f32_e32 v211, v211, v212
	v_add_f32_e32 v210, v210, v211
	v_mul_f32_e32 v211, v7, v7
	v_mul_f32_e32 v212, v9, v9
	v_fmac_f32_e32 v211, v6, v6
	v_fmac_f32_e32 v212, v8, v8
	v_add_f32_e32 v211, v211, v212
	v_add_f32_e32 v210, v210, v211
	v_mul_f32_e32 v211, v3, v3
	v_mul_f32_e32 v212, v5, v5
	v_fmac_f32_e32 v211, v2, v2
	v_fmac_f32_e32 v212, v4, v4
	v_add_f32_e32 v211, v211, v212
	v_add_f32_e32 v210, v210, v211
	v_mov_b32_e32 v211, v210
	s_nop 1
	v_permlane16_swap_b32_e32 v211, v210
	s_waitcnt lgkmcnt(0)
	v_add_f32_e32 v214, v210, v211
	v_mov_b32_e32 v215, v214
	s_nop 1
	v_permlane32_swap_b32_e32 v215, v214
	s_and_saveexec_b64 s[10:11], s[0:1]
	s_cbranch_execz .LBB0_483
	s_waitcnt lgkmcnt(0)
	v_add_f32_e32 v210, v214, v215
	ds_write_b32 v230, v210 offset:2816

;     __device__ __forceinline__ void operator()(const f32x4 (&acc)[2][2][4][2], const pg8::Unit& u, int wr, int wc, int fr, int fq, LAS unsigned char* lds, int wid, int lane, const pg8::Unit& nxt, bool has_next, int ui) const {
;     ...
; #pragma unroll
;         for (int m = 0; m < 4; ++m) { RESNORM_ROWGROUP(0, m);
.LBB0_489:
	s_or_b64 exec, exec, s[70:71]
	s_waitcnt lgkmcnt(0)
	s_barrier
	ds_read_b32 v210, v231
	s_waitcnt lgkmcnt(0)
	v_pk_mul_f32 v[142:143], v[142:143], v[210:211] op_sel_hi:[1,0]
	v_pk_mul_f32 v[144:145], v[144:145], v[210:211] op_sel_hi:[1,0]
	s_waitcnt vmcnt(0)
	v_pk_mul_f32 v[142:143], v[106:107], v[142:143]
	v_pk_mul_f32 v[140:141], v[140:141], v[210:211] op_sel_hi:[1,0]
	v_pk_mul_f32 v[138:139], v[138:139], v[210:211] op_sel_hi:[1,0]
	v_lshlrev_b32_e32 v211, 16, v174
	v_and_b32_e32 v174, 0xffff0000, v174
	v_pk_mul_f32 v[144:145], v[108:109], v[144:145]
	v_add_f32_e32 v143, v143, v174
	v_lshlrev_b32_e32 v174, 16, v175
	v_add_f32_e32 v144, v144, v174
	v_and_b32_e32 v174, 0xffff0000, v175
	v_pk_mul_f32 v[138:139], v[98:99], v[138:139]
	v_add_f32_e32 v145, v145, v174
	v_lshlrev_b32_e32 v174, 16, v176
	v_add_f32_e32 v138, v138, v174
	v_and_b32_e32 v174, 0xffff0000, v176
	v_pk_mul_f32 v[140:141], v[100:101], v[140:141]
	v_add_f32_e32 v139, v139, v174
	v_lshlrev_b32_e32 v174, 16, v177
	v_add_f32_e32 v142, v142, v211
	v_add_f32_e32 v174, v140, v174
	v_and_b32_e32 v140, 0xffff0000, v177
	v_add_f32_e32 v175, v141, v140
	v_cvt_pk_bf16_f32 v140, v142, v143
	v_cvt_pk_bf16_f32 v141, v144, v145
	v_cvt_pk_bf16_f32 v142, v138, v139
	v_cvt_pk_bf16_f32 v143, v174, v175
	v_pk_mul_f32 v[134:135], v[134:135], v[210:211] op_sel_hi:[1,0]
	v_and_b32_e32 v139, 0xffff0000, v140
	v_lshlrev_b32_e32 v138, 16, v140
	v_mul_f32_e32 v139, v139, v139
	v_and_b32_e32 v144, 0xffff0000, v141
	v_fmac_f32_e32 v139, v138, v138
	v_lshlrev_b32_e32 v138, 16, v141
	v_mul_f32_e32 v144, v144, v144
	v_fmac_f32_e32 v144, v138, v138
	v_add_f32_e32 v138, v139, v144
	v_and_b32_e32 v144, 0xffff0000, v142
	v_lshlrev_b32_e32 v139, 16, v142
	v_mul_f32_e32 v144, v144, v144
	v_fmac_f32_e32 v144, v139, v139
	v_add_f32_e32 v138, v138, v144
	v_and_b32_e32 v144, 0xffff0000, v143
	v_lshlrev_b32_e32 v139, 16, v143
	v_mul_f32_e32 v144, v144, v144
	v_fmac_f32_e32 v144, v139, v139
	v_add_f32_e32 v174, v138, v144
	v_lshl_add_u64 v[138:139], s[36:37], 0, v[216:217]
	v_lshl_add_u64 v[144:145], v[208:209], 1, v[138:139]
	global_store_dwordx4 v[144:145], v[140:143], off
	v_pk_mul_f32 v[134:135], v[94:95], v[134:135]
	v_pk_mul_f32 v[136:137], v[136:137], v[210:211] op_sel_hi:[1,0]
	v_lshlrev_b32_e32 v140, 16, v170
	v_add_f32_e32 v134, v134, v140
	v_and_b32_e32 v140, 0xffff0000, v170
	v_pk_mul_f32 v[136:137], v[96:97], v[136:137]
	v_add_f32_e32 v135, v135, v140
	v_lshlrev_b32_e32 v140, 16, v171
	v_pk_mul_f32 v[130:131], v[130:131], v[210:211] op_sel_hi:[1,0]
	v_add_f32_e32 v136, v136, v140
	v_and_b32_e32 v140, 0xffff0000, v171
	v_pk_mul_f32 v[130:131], v[90:91], v[130:131]
	v_add_f32_e32 v137, v137, v140
	v_lshlrev_b32_e32 v140, 16, v172
	v_pk_mul_f32 v[132:133], v[132:133], v[210:211] op_sel_hi:[1,0]
	v_add_f32_e32 v130, v130, v140
	v_and_b32_e32 v140, 0xffff0000, v172
	v_pk_mul_f32 v[132:133], v[92:93], v[132:133]
	v_add_f32_e32 v131, v131, v140
	v_lshlrev_b32_e32 v140, 16, v173
	v_add_f32_e32 v140, v132, v140
	v_and_b32_e32 v132, 0xffff0000, v173
	v_add_f32_e32 v141, v133, v132
	v_cvt_pk_bf16_f32 v132, v134, v135
	v_cvt_pk_bf16_f32 v133, v136, v137
	v_cvt_pk_bf16_f32 v134, v130, v131
	v_cvt_pk_bf16_f32 v135, v140, v141
	global_store_dwordx4 v[144:145], v[132:135], off offset:256
	v_and_b32_e32 v131, 0xffff0000, v132
	v_lshlrev_b32_e32 v130, 16, v132
	v_mul_f32_e32 v131, v131, v131
	v_fmac_f32_e32 v131, v130, v130
	v_and_b32_e32 v136, 0xffff0000, v133
	v_add_f32_e32 v130, v174, v131
	v_lshlrev_b32_e32 v131, 16, v133
	v_mul_f32_e32 v136, v136, v136
	v_fmac_f32_e32 v136, v131, v131
	v_add_f32_e32 v130, v130, v136
	v_and_b32_e32 v136, 0xffff0000, v134
	v_lshlrev_b32_e32 v131, 16, v134
	v_mul_f32_e32 v136, v136, v136
	v_fmac_f32_e32 v136, v131, v131
	v_add_f32_e32 v130, v130, v136
	v_and_b32_e32 v136, 0xffff0000, v135
	v_lshlrev_b32_e32 v131, 16, v135
	v_mul_f32_e32 v136, v136, v136
	v_fmac_f32_e32 v136, v131, v131
	v_add_f32_e32 v130, v130, v136
	v_mov_b32_e32 v131, v130
	s_nop 1
	v_permlane16_swap_b32_e32 v131, v130
	s_waitcnt lgkmcnt(0)
	v_add_f32_e32 v130, v130, v131
	v_mov_b32_e32 v131, v130
	s_nop 1
	v_permlane32_swap_b32_e32 v131, v130
	s_and_saveexec_b64 s[10:11], s[0:1]
	s_cbranch_execz .LBB0_491
	s_waitcnt lgkmcnt(0)
	v_add_f32_e32 v130, v130, v131
	v_add_u32_e32 v131, s12, v229
	ds_write_b32 v131, v130
;     __device__ __forceinline__ void operator()(const f32x4 (&acc)[2][2][4][2], const pg8::Unit& u, int wr, int wc, int fr, int fq, LAS unsigned char* lds, int wid, int lane, const pg8::Unit& nxt, bool has_next, int ui) const {
;     ...
; #pragma unroll
;         for (int m = 0; m < 4; ++m) { RESNORM_ROWGROUP(0, m);
; #pragma unroll
;             for (int bj = 0; bj < 2; ++bj) xv[m][bj] = *(const v4u*)(X + (rowbase + rl0 + 128 + m * 16) * DM + col0 + bj * 128); }
.LBB0_491:
	s_or_b64 exec, exec, s[10:11]
	s_mov_b64 s[10:11], 0x40000
	s_waitcnt lgkmcnt(0)
	v_lshl_add_u64 v[130:131], v[138:139], 0, s[10:11]
	v_lshlrev_b64 v[138:139], 1, v[208:209]
	v_lshl_add_u64 v[140:141], v[130:131], 0, v[138:139]
	v_lshl_add_u32 v130, v190, 2, s56
	ds_read_b32 v142, v130
	global_load_dwordx4 v[134:137], v[140:141], off
	global_load_dwordx4 v[130:133], v[140:141], off offset:256
	v_lshl_add_u64 v[144:145], s[30:31], 0, v[190:191]
	v_lshlrev_b64 v[144:145], 11, v[144:145]
	s_waitcnt lgkmcnt(0)
	v_pk_mul_f32 v[126:127], v[126:127], v[142:143] op_sel_hi:[1,0]
	v_pk_mul_f32 v[128:129], v[128:129], v[142:143] op_sel_hi:[1,0]
	v_pk_mul_f32 v[126:127], v[106:107], v[126:127]
	v_pk_mul_f32 v[124:125], v[124:125], v[142:143] op_sel_hi:[1,0]
	v_pk_mul_f32 v[122:123], v[122:123], v[142:143] op_sel_hi:[1,0]
	v_lshlrev_b32_e32 v143, 16, v166
	v_add_f32_e32 v126, v126, v143
	v_and_b32_e32 v143, 0xffff0000, v166
	v_pk_mul_f32 v[128:129], v[108:109], v[128:129]
	v_add_f32_e32 v127, v127, v143
	v_lshlrev_b32_e32 v143, 16, v167
	v_add_f32_e32 v128, v128, v143
	v_and_b32_e32 v143, 0xffff0000, v167
	v_pk_mul_f32 v[122:123], v[98:99], v[122:123]
	v_add_f32_e32 v129, v129, v143
	v_lshlrev_b32_e32 v143, 16, v168
	v_add_f32_e32 v143, v122, v143
	v_and_b32_e32 v122, 0xffff0000, v168
	v_pk_mul_f32 v[124:125], v[100:101], v[124:125]
	v_add_f32_e32 v166, v123, v122
	v_lshlrev_b32_e32 v122, 16, v169
	v_add_f32_e32 v167, v124, v122
	v_and_b32_e32 v122, 0xffff0000, v169
	v_add_f32_e32 v125, v125, v122
	v_cvt_pk_bf16_f32 v122, v126, v127
	v_cvt_pk_bf16_f32 v123, v128, v129
	v_cvt_pk_bf16_f32 v124, v143, v166
	v_cvt_pk_bf16_f32 v125, v167, v125
	v_pk_mul_f32 v[118:119], v[118:119], v[142:143] op_sel_hi:[1,0]
	v_and_b32_e32 v127, 0xffff0000, v122
	v_lshlrev_b32_e32 v126, 16, v122
	v_mul_f32_e32 v127, v127, v127
	v_and_b32_e32 v128, 0xffff0000, v123
	v_fmac_f32_e32 v127, v126, v126
	v_lshlrev_b32_e32 v126, 16, v123
	v_mul_f32_e32 v128, v128, v128
	v_fmac_f32_e32 v128, v126, v126
	v_add_f32_e32 v126, v127, v128
	v_and_b32_e32 v128, 0xffff0000, v124
	v_lshlrev_b32_e32 v127, 16, v124
	v_mul_f32_e32 v128, v128, v128
	v_fmac_f32_e32 v128, v127, v127
	v_add_f32_e32 v126, v126, v128
	v_and_b32_e32 v128, 0xffff0000, v125
	v_lshlrev_b32_e32 v127, 16, v125
	v_mul_f32_e32 v128, v128, v128
	v_fmac_f32_e32 v128, v127, v127
	v_add_f32_e32 v128, v126, v128
	v_lshl_add_u64 v[126:127], s[36:37], 0, v[144:145]
	v_lshl_add_u64 v[126:127], v[126:127], 0, v[138:139]
	global_store_dwordx4 v[126:127], v[122:125], off
	v_pk_mul_f32 v[118:119], v[94:95], v[118:119]
	v_pk_mul_f32 v[120:121], v[120:121], v[142:143] op_sel_hi:[1,0]
	v_lshlrev_b32_e32 v122, 16, v162
	v_add_f32_e32 v118, v118, v122
	v_and_b32_e32 v122, 0xffff0000, v162
	v_pk_mul_f32 v[120:121], v[96:97], v[120:121]
	v_add_f32_e32 v119, v119, v122
	v_lshlrev_b32_e32 v122, 16, v163
	v_pk_mul_f32 v[114:115], v[114:115], v[142:143] op_sel_hi:[1,0]
	v_add_f32_e32 v120, v120, v122
	v_and_b32_e32 v122, 0xffff0000, v163
	v_pk_mul_f32 v[114:115], v[90:91], v[114:115]
	v_add_f32_e32 v121, v121, v122
	v_lshlrev_b32_e32 v122, 16, v164
	v_pk_mul_f32 v[116:117], v[116:117], v[142:143] op_sel_hi:[1,0]
	v_add_f32_e32 v114, v114, v122
	v_and_b32_e32 v122, 0xffff0000, v164
	v_pk_mul_f32 v[116:117], v[92:93], v[116:117]
	v_add_f32_e32 v115, v115, v122
	v_lshlrev_b32_e32 v122, 16, v165
	v_add_f32_e32 v122, v116, v122
	v_and_b32_e32 v116, 0xffff0000, v165
	v_add_f32_e32 v123, v117, v116
	v_cvt_pk_bf16_f32 v116, v118, v119
	v_cvt_pk_bf16_f32 v117, v120, v121
	v_cvt_pk_bf16_f32 v118, v114, v115
	v_cvt_pk_bf16_f32 v119, v122, v123
	global_store_dwordx4 v[126:127], v[116:119], off offset:256
	v_and_b32_e32 v115, 0xffff0000, v116
	v_lshlrev_b32_e32 v114, 16, v116
	v_mul_f32_e32 v115, v115, v115
	v_fmac_f32_e32 v115, v114, v114
	v_and_b32_e32 v120, 0xffff0000, v117
	v_add_f32_e32 v114, v128, v115
	v_lshlrev_b32_e32 v115, 16, v117
	v_mul_f32_e32 v120, v120, v120
	v_fmac_f32_e32 v120, v115, v115
	v_add_f32_e32 v114, v114, v120
	v_and_b32_e32 v120, 0xffff0000, v118
	v_lshlrev_b32_e32 v115, 16, v118
	v_mul_f32_e32 v120, v120, v120
	v_fmac_f32_e32 v120, v115, v115
	v_add_f32_e32 v114, v114, v120
	v_and_b32_e32 v120, 0xffff0000, v119
	v_lshlrev_b32_e32 v115, 16, v119
	v_mul_f32_e32 v120, v120, v120
	v_fmac_f32_e32 v120, v115, v115
	v_add_f32_e32 v114, v114, v120
	v_mov_b32_e32 v115, v114
	s_nop 1
	v_permlane16_swap_b32_e32 v115, v114
	s_waitcnt lgkmcnt(0)
	v_add_f32_e32 v114, v114, v115
	v_mov_b32_e32 v115, v114
	s_nop 1
	v_permlane32_swap_b32_e32 v115, v114
	s_and_saveexec_b64 s[10:11], s[0:1]
	s_cbranch_execz .LBB0_493
	s_waitcnt lgkmcnt(0)
	v_add_f32_e32 v114, v114, v115
	ds_write_b32 v233, v114
;     __device__ __forceinline__ void operator()(const f32x4 (&acc)[2][2][4][2], const pg8::Unit& u, int wr, int wc, int fr, int fq, LAS unsigned char* lds, int wid, int lane, const pg8::Unit& nxt, bool has_next, int ui) const {
;     ...
; #pragma unroll
;         for (int m = 0; m < 4; ++m) { RESNORM_ROWGROUP(0, m);
; #pragma unroll
;             for (int bj = 0; bj < 2; ++bj) xv[m][bj] = *(const v4u*)(X + (rowbase + rl0 + 128 + m * 16) * DM + col0 + bj * 128); }
.LBB0_493:
	s_or_b64 exec, exec, s[10:11]
	s_mov_b64 s[10:11], 0x8000
	v_add_co_u32_e32 v116, vcc, 0x8000, v140
	s_waitcnt lgkmcnt(0)
	v_lshl_add_u64 v[114:115], v[140:141], 0, s[10:11]
	v_addc_co_u32_e32 v117, vcc, 0, v141, vcc
	v_lshl_add_u32 v118, v192, 2, s56
	ds_read_b32 v122, v118
	global_load_dwordx4 v[118:121], v[116:117], off
	s_nop 0
	global_load_dwordx4 v[114:117], v[114:115], off offset:256
	v_lshl_add_u64 v[124:125], s[30:31], 0, v[192:193]
	v_lshlrev_b64 v[124:125], 11, v[124:125]
	s_waitcnt lgkmcnt(0)
	v_pk_mul_f32 v[110:111], v[110:111], v[122:123] op_sel_hi:[1,0]
	v_pk_mul_f32 v[112:113], v[112:113], v[122:123] op_sel_hi:[1,0]
	v_pk_mul_f32 v[110:111], v[106:107], v[110:111]
	v_pk_mul_f32 v[104:105], v[104:105], v[122:123] op_sel_hi:[1,0]
	v_pk_mul_f32 v[102:103], v[102:103], v[122:123] op_sel_hi:[1,0]
	v_lshlrev_b32_e32 v123, 16, v158
	v_add_f32_e32 v110, v110, v123
	v_and_b32_e32 v123, 0xffff0000, v158
	v_pk_mul_f32 v[112:113], v[108:109], v[112:113]
	v_add_f32_e32 v111, v111, v123
	v_lshlrev_b32_e32 v123, 16, v159
	v_add_f32_e32 v112, v112, v123
	v_and_b32_e32 v123, 0xffff0000, v159
	v_pk_mul_f32 v[102:103], v[98:99], v[102:103]
	v_add_f32_e32 v113, v113, v123
	v_lshlrev_b32_e32 v123, 16, v160
	v_add_f32_e32 v123, v102, v123
	v_and_b32_e32 v102, 0xffff0000, v160
	v_pk_mul_f32 v[104:105], v[100:101], v[104:105]
	v_add_f32_e32 v126, v103, v102
	v_lshlrev_b32_e32 v102, 16, v161
	v_add_f32_e32 v127, v104, v102
	v_and_b32_e32 v102, 0xffff0000, v161
	v_add_f32_e32 v105, v105, v102
	v_cvt_pk_bf16_f32 v102, v110, v111
	v_cvt_pk_bf16_f32 v103, v112, v113
	v_cvt_pk_bf16_f32 v104, v123, v126
	v_cvt_pk_bf16_f32 v105, v127, v105
	v_pk_mul_f32 v[86:87], v[86:87], v[122:123] op_sel_hi:[1,0]
	v_and_b32_e32 v111, 0xffff0000, v102
	v_lshlrev_b32_e32 v110, 16, v102
	v_mul_f32_e32 v111, v111, v111
	v_and_b32_e32 v112, 0xffff0000, v103
	v_fmac_f32_e32 v111, v110, v110
	v_lshlrev_b32_e32 v110, 16, v103
	v_mul_f32_e32 v112, v112, v112
	v_fmac_f32_e32 v112, v110, v110
	v_add_f32_e32 v110, v111, v112
	v_and_b32_e32 v112, 0xffff0000, v104
	v_lshlrev_b32_e32 v111, 16, v104
	v_mul_f32_e32 v112, v112, v112
	v_fmac_f32_e32 v112, v111, v111
	v_add_f32_e32 v110, v110, v112
	v_and_b32_e32 v112, 0xffff0000, v105
	v_lshlrev_b32_e32 v111, 16, v105
	v_mul_f32_e32 v112, v112, v112
	v_fmac_f32_e32 v112, v111, v111
	v_add_f32_e32 v112, v110, v112
	v_lshl_add_u64 v[110:111], s[36:37], 0, v[124:125]
	v_lshl_add_u64 v[110:111], v[110:111], 0, v[138:139]
	global_store_dwordx4 v[110:111], v[102:105], off
	v_pk_mul_f32 v[86:87], v[94:95], v[86:87]
	v_pk_mul_f32 v[88:89], v[88:89], v[122:123] op_sel_hi:[1,0]
	v_lshlrev_b32_e32 v102, 16, v154
	v_add_f32_e32 v86, v86, v102
	v_and_b32_e32 v102, 0xffff0000, v154
	v_pk_mul_f32 v[88:89], v[96:97], v[88:89]
	v_add_f32_e32 v87, v87, v102
	v_lshlrev_b32_e32 v102, 16, v155
	v_pk_mul_f32 v[82:83], v[82:83], v[122:123] op_sel_hi:[1,0]
	v_add_f32_e32 v88, v88, v102
	v_and_b32_e32 v102, 0xffff0000, v155
	v_pk_mul_f32 v[82:83], v[90:91], v[82:83]
	v_add_f32_e32 v89, v89, v102
	v_lshlrev_b32_e32 v102, 16, v156
	v_pk_mul_f32 v[84:85], v[84:85], v[122:123] op_sel_hi:[1,0]
	v_add_f32_e32 v82, v82, v102
	v_and_b32_e32 v102, 0xffff0000, v156
	v_pk_mul_f32 v[84:85], v[92:93], v[84:85]
	v_add_f32_e32 v83, v83, v102
	v_lshlrev_b32_e32 v102, 16, v157
	v_add_f32_e32 v102, v84, v102
	v_and_b32_e32 v84, 0xffff0000, v157
	v_add_f32_e32 v103, v85, v84
	v_cvt_pk_bf16_f32 v84, v86, v87
	v_cvt_pk_bf16_f32 v85, v88, v89
	v_cvt_pk_bf16_f32 v86, v82, v83
	v_cvt_pk_bf16_f32 v87, v102, v103
	global_store_dwordx4 v[110:111], v[84:87], off offset:256
	v_and_b32_e32 v83, 0xffff0000, v84
	v_lshlrev_b32_e32 v82, 16, v84
	v_mul_f32_e32 v83, v83, v83
	v_fmac_f32_e32 v83, v82, v82
	v_and_b32_e32 v88, 0xffff0000, v85
	v_add_f32_e32 v82, v112, v83
	v_lshlrev_b32_e32 v83, 16, v85
	v_mul_f32_e32 v88, v88, v88
	v_fmac_f32_e32 v88, v83, v83
	v_add_f32_e32 v82, v82, v88
	v_and_b32_e32 v88, 0xffff0000, v86
	v_lshlrev_b32_e32 v83, 16, v86
	v_mul_f32_e32 v88, v88, v88
	v_fmac_f32_e32 v88, v83, v83
	v_add_f32_e32 v82, v82, v88
	v_and_b32_e32 v88, 0xffff0000, v87
	v_lshlrev_b32_e32 v83, 16, v87
	v_mul_f32_e32 v88, v88, v88
	v_fmac_f32_e32 v88, v83, v83
	v_add_f32_e32 v82, v82, v88
	v_mov_b32_e32 v83, v82
	s_nop 1
	v_permlane16_swap_b32_e32 v83, v82
	s_waitcnt lgkmcnt(0)
	v_add_f32_e32 v82, v82, v83
	v_mov_b32_e32 v83, v82
	s_nop 1
	v_permlane32_swap_b32_e32 v83, v82
	s_and_saveexec_b64 s[10:11], s[0:1]
	s_cbranch_execz .LBB0_495
	s_waitcnt lgkmcnt(0)
	v_add_f32_e32 v82, v82, v83
	ds_write_b32 v234, v82
;     __device__ __forceinline__ void operator()(const f32x4 (&acc)[2][2][4][2], const pg8::Unit& u, int wr, int wc, int fr, int fq, LAS unsigned char* lds, int wid, int lane, const pg8::Unit& nxt, bool has_next, int ui) const {
;     ...
; #pragma unroll
;         for (int m = 0; m < 4; ++m) { RESNORM_ROWGROUP(0, m);
; #pragma unroll
;             for (int bj = 0; bj < 2; ++bj) xv[m][bj] = *(const v4u*)(X + (rowbase + rl0 + 128 + m * 16) * DM + col0 + bj * 128); }
.LBB0_495:
	s_or_b64 exec, exec, s[10:11]
	s_mov_b64 s[10:11], 0x10000
	v_add_co_u32_e32 v84, vcc, 0x10000, v140
	s_waitcnt lgkmcnt(0)
	v_lshl_add_u64 v[82:83], v[140:141], 0, s[10:11]
	v_addc_co_u32_e32 v85, vcc, 0, v141, vcc
	v_lshl_add_u32 v86, v194, 2, s56
	ds_read_b32 v102, v86
	global_load_dwordx4 v[86:89], v[84:85], off
	s_nop 0
	global_load_dwordx4 v[82:85], v[82:83], off offset:256
	v_lshl_add_u64 v[104:105], s[30:31], 0, v[194:195]
	v_lshlrev_b64 v[104:105], 11, v[104:105]
	s_waitcnt lgkmcnt(0)
	v_pk_mul_f32 v[78:79], v[78:79], v[102:103] op_sel_hi:[1,0]
	v_pk_mul_f32 v[80:81], v[80:81], v[102:103] op_sel_hi:[1,0]
	v_pk_mul_f32 v[78:79], v[106:107], v[78:79]
	v_pk_mul_f32 v[76:77], v[76:77], v[102:103] op_sel_hi:[1,0]
	v_pk_mul_f32 v[74:75], v[74:75], v[102:103] op_sel_hi:[1,0]
	v_lshlrev_b32_e32 v103, 16, v150
	v_add_f32_e32 v78, v78, v103
	v_and_b32_e32 v103, 0xffff0000, v150
	v_pk_mul_f32 v[80:81], v[108:109], v[80:81]
	v_add_f32_e32 v79, v79, v103
	v_lshlrev_b32_e32 v103, 16, v151
	v_add_f32_e32 v80, v80, v103
	v_and_b32_e32 v103, 0xffff0000, v151
	v_pk_mul_f32 v[74:75], v[98:99], v[74:75]
	v_add_f32_e32 v81, v81, v103
	v_lshlrev_b32_e32 v103, 16, v152
	v_add_f32_e32 v103, v74, v103
	v_and_b32_e32 v74, 0xffff0000, v152
	v_pk_mul_f32 v[76:77], v[100:101], v[76:77]
	v_add_f32_e32 v110, v75, v74
	v_lshlrev_b32_e32 v74, 16, v153
	v_add_f32_e32 v111, v76, v74
	v_and_b32_e32 v74, 0xffff0000, v153
	v_add_f32_e32 v77, v77, v74
	v_cvt_pk_bf16_f32 v74, v78, v79
	v_cvt_pk_bf16_f32 v75, v80, v81
	v_cvt_pk_bf16_f32 v76, v103, v110
	v_cvt_pk_bf16_f32 v77, v111, v77
	v_pk_mul_f32 v[70:71], v[70:71], v[102:103] op_sel_hi:[1,0]
	v_and_b32_e32 v79, 0xffff0000, v74
	v_lshlrev_b32_e32 v78, 16, v74
	v_mul_f32_e32 v79, v79, v79
	v_and_b32_e32 v80, 0xffff0000, v75
	v_fmac_f32_e32 v79, v78, v78
	v_lshlrev_b32_e32 v78, 16, v75
	v_mul_f32_e32 v80, v80, v80
	v_fmac_f32_e32 v80, v78, v78
	v_add_f32_e32 v78, v79, v80
	v_and_b32_e32 v80, 0xffff0000, v76
	v_lshlrev_b32_e32 v79, 16, v76
	v_mul_f32_e32 v80, v80, v80
	v_fmac_f32_e32 v80, v79, v79
	v_add_f32_e32 v78, v78, v80
	v_and_b32_e32 v80, 0xffff0000, v77
	v_lshlrev_b32_e32 v79, 16, v77
	v_mul_f32_e32 v80, v80, v80
	v_fmac_f32_e32 v80, v79, v79
	v_add_f32_e32 v80, v78, v80
	v_lshl_add_u64 v[78:79], s[36:37], 0, v[104:105]
	v_lshl_add_u64 v[78:79], v[78:79], 0, v[138:139]
	global_store_dwordx4 v[78:79], v[74:77], off
	v_pk_mul_f32 v[70:71], v[94:95], v[70:71]
	v_pk_mul_f32 v[72:73], v[72:73], v[102:103] op_sel_hi:[1,0]
	v_lshlrev_b32_e32 v74, 16, v146
	v_add_f32_e32 v70, v70, v74
	v_and_b32_e32 v74, 0xffff0000, v146
	v_pk_mul_f32 v[72:73], v[96:97], v[72:73]
	v_add_f32_e32 v71, v71, v74
	v_lshlrev_b32_e32 v74, 16, v147
	v_pk_mul_f32 v[66:67], v[66:67], v[102:103] op_sel_hi:[1,0]
	v_add_f32_e32 v72, v72, v74
	v_and_b32_e32 v74, 0xffff0000, v147
	v_pk_mul_f32 v[66:67], v[90:91], v[66:67]
	v_add_f32_e32 v73, v73, v74
	v_lshlrev_b32_e32 v74, 16, v148
	v_pk_mul_f32 v[68:69], v[68:69], v[102:103] op_sel_hi:[1,0]
	v_add_f32_e32 v66, v66, v74
	v_and_b32_e32 v74, 0xffff0000, v148
	v_pk_mul_f32 v[68:69], v[92:93], v[68:69]
	v_add_f32_e32 v67, v67, v74
	v_lshlrev_b32_e32 v74, 16, v149
	v_add_f32_e32 v74, v68, v74
	v_and_b32_e32 v68, 0xffff0000, v149
	v_add_f32_e32 v75, v69, v68
	v_cvt_pk_bf16_f32 v68, v70, v71
	v_cvt_pk_bf16_f32 v69, v72, v73
	v_cvt_pk_bf16_f32 v70, v66, v67
	v_cvt_pk_bf16_f32 v71, v74, v75
	global_store_dwordx4 v[78:79], v[68:71], off offset:256
	v_and_b32_e32 v67, 0xffff0000, v68
	v_lshlrev_b32_e32 v66, 16, v68
	v_mul_f32_e32 v67, v67, v67
	v_fmac_f32_e32 v67, v66, v66
	v_and_b32_e32 v72, 0xffff0000, v69
	v_add_f32_e32 v66, v80, v67
	v_lshlrev_b32_e32 v67, 16, v69
	v_mul_f32_e32 v72, v72, v72
	v_fmac_f32_e32 v72, v67, v67
	v_add_f32_e32 v66, v66, v72
	v_and_b32_e32 v72, 0xffff0000, v70
	v_lshlrev_b32_e32 v67, 16, v70
	v_mul_f32_e32 v72, v72, v72
	v_fmac_f32_e32 v72, v67, v67
	v_add_f32_e32 v66, v66, v72
	v_and_b32_e32 v72, 0xffff0000, v71
	v_lshlrev_b32_e32 v67, 16, v71
	v_mul_f32_e32 v72, v72, v72
	v_fmac_f32_e32 v72, v67, v67
	v_add_f32_e32 v66, v66, v72
	v_mov_b32_e32 v67, v66
	s_nop 1
	v_permlane16_swap_b32_e32 v67, v66
	s_waitcnt lgkmcnt(0)
	v_add_f32_e32 v66, v66, v67
	v_mov_b32_e32 v67, v66
	s_nop 1
	v_permlane32_swap_b32_e32 v67, v66
	s_and_saveexec_b64 s[10:11], s[0:1]
	s_cbranch_execz .LBB0_497
	s_waitcnt lgkmcnt(0)
	v_add_f32_e32 v66, v66, v67
	ds_write_b32 v235, v66
;     __device__ __forceinline__ void operator()(const f32x4 (&acc)[2][2][4][2], const pg8::Unit& u, int wr, int wc, int fr, int fq, LAS unsigned char* lds, int wid, int lane, const pg8::Unit& nxt, bool has_next, int ui) const {
;     ...
; #pragma unroll
;         for (int m = 0; m < 4; ++m) { RESNORM_ROWGROUP(0, m);
; #pragma unroll
;             for (int bj = 0; bj < 2; ++bj) xv[m][bj] = *(const v4u*)(X + (rowbase + rl0 + 128 + m * 16) * DM + col0 + bj * 128); }
; #pragma unroll
;         for (int m = 0; m < 4; ++m) RESNORM_ROWGROUP(1, m);
.LBB0_497:
	s_or_b64 exec, exec, s[10:11]
	s_mov_b64 s[10:11], 0x18000
	v_add_co_u32_e32 v68, vcc, 0x18000, v140
	s_waitcnt lgkmcnt(0)
	v_lshl_add_u64 v[66:67], v[140:141], 0, s[10:11]
	v_addc_co_u32_e32 v69, vcc, 0, v141, vcc
	v_lshl_add_u32 v70, v196, 2, s56
	ds_read_b32 v74, v70
	global_load_dwordx4 v[70:73], v[68:69], off
	s_nop 0
	global_load_dwordx4 v[66:69], v[66:67], off offset:256
	v_lshl_add_u64 v[76:77], s[30:31], 0, v[196:197]
	v_lshlrev_b64 v[76:77], 11, v[76:77]
	s_waitcnt lgkmcnt(0)
	v_pk_mul_f32 v[62:63], v[62:63], v[74:75] op_sel_hi:[1,0]
	v_pk_mul_f32 v[64:65], v[64:65], v[74:75] op_sel_hi:[1,0]
	v_pk_mul_f32 v[62:63], v[106:107], v[62:63]
	v_pk_mul_f32 v[60:61], v[60:61], v[74:75] op_sel_hi:[1,0]
	v_pk_mul_f32 v[58:59], v[58:59], v[74:75] op_sel_hi:[1,0]
	s_waitcnt vmcnt(13)
	v_lshlrev_b32_e32 v75, 16, v134
	v_add_f32_e32 v62, v62, v75
	v_and_b32_e32 v75, 0xffff0000, v134
	v_pk_mul_f32 v[64:65], v[108:109], v[64:65]
	v_add_f32_e32 v63, v63, v75
	v_lshlrev_b32_e32 v75, 16, v135
	v_add_f32_e32 v64, v64, v75
	v_and_b32_e32 v75, 0xffff0000, v135
	v_pk_mul_f32 v[58:59], v[98:99], v[58:59]
	v_add_f32_e32 v65, v65, v75
	v_lshlrev_b32_e32 v75, 16, v136
	v_add_f32_e32 v75, v58, v75
	v_and_b32_e32 v58, 0xffff0000, v136
	v_pk_mul_f32 v[60:61], v[100:101], v[60:61]
	v_add_f32_e32 v78, v59, v58
	v_lshlrev_b32_e32 v58, 16, v137
	v_add_f32_e32 v79, v60, v58
	v_and_b32_e32 v58, 0xffff0000, v137
	v_add_f32_e32 v61, v61, v58
	v_cvt_pk_bf16_f32 v58, v62, v63
	v_cvt_pk_bf16_f32 v59, v64, v65
	v_cvt_pk_bf16_f32 v60, v75, v78
	v_cvt_pk_bf16_f32 v61, v79, v61
	v_pk_mul_f32 v[54:55], v[54:55], v[74:75] op_sel_hi:[1,0]
	v_and_b32_e32 v63, 0xffff0000, v58
	v_lshlrev_b32_e32 v62, 16, v58
	v_mul_f32_e32 v63, v63, v63
	v_and_b32_e32 v64, 0xffff0000, v59
	v_fmac_f32_e32 v63, v62, v62
	v_lshlrev_b32_e32 v62, 16, v59
	v_mul_f32_e32 v64, v64, v64
	v_fmac_f32_e32 v64, v62, v62
	v_add_f32_e32 v62, v63, v64
	v_and_b32_e32 v64, 0xffff0000, v60
	v_lshlrev_b32_e32 v63, 16, v60
	v_mul_f32_e32 v64, v64, v64
	v_fmac_f32_e32 v64, v63, v63
	v_add_f32_e32 v62, v62, v64
	v_and_b32_e32 v64, 0xffff0000, v61
	v_lshlrev_b32_e32 v63, 16, v61
	v_mul_f32_e32 v64, v64, v64
	v_fmac_f32_e32 v64, v63, v63
	v_add_f32_e32 v64, v62, v64
	v_lshl_add_u64 v[62:63], s[36:37], 0, v[76:77]
	v_lshl_add_u64 v[62:63], v[62:63], 0, v[138:139]
	global_store_dwordx4 v[62:63], v[58:61], off
	v_pk_mul_f32 v[54:55], v[94:95], v[54:55]
	v_pk_mul_f32 v[56:57], v[56:57], v[74:75] op_sel_hi:[1,0]
	s_waitcnt vmcnt(13)
	v_lshlrev_b32_e32 v58, 16, v130
	v_add_f32_e32 v54, v54, v58
	v_and_b32_e32 v58, 0xffff0000, v130
	v_pk_mul_f32 v[56:57], v[96:97], v[56:57]
	v_add_f32_e32 v55, v55, v58
	v_lshlrev_b32_e32 v58, 16, v131
	v_pk_mul_f32 v[50:51], v[50:51], v[74:75] op_sel_hi:[1,0]
	v_add_f32_e32 v56, v56, v58
	v_and_b32_e32 v58, 0xffff0000, v131
	v_pk_mul_f32 v[50:51], v[90:91], v[50:51]
	v_add_f32_e32 v57, v57, v58
	v_lshlrev_b32_e32 v58, 16, v132
	v_pk_mul_f32 v[52:53], v[52:53], v[74:75] op_sel_hi:[1,0]
	v_add_f32_e32 v50, v50, v58
	v_and_b32_e32 v58, 0xffff0000, v132
	v_pk_mul_f32 v[52:53], v[92:93], v[52:53]
	v_add_f32_e32 v51, v51, v58
	v_lshlrev_b32_e32 v58, 16, v133
	v_add_f32_e32 v58, v52, v58
	v_and_b32_e32 v52, 0xffff0000, v133
	v_add_f32_e32 v59, v53, v52
	v_cvt_pk_bf16_f32 v52, v54, v55
	v_cvt_pk_bf16_f32 v53, v56, v57
	v_cvt_pk_bf16_f32 v54, v50, v51
	v_cvt_pk_bf16_f32 v55, v58, v59
	global_store_dwordx4 v[62:63], v[52:55], off offset:256
	v_and_b32_e32 v51, 0xffff0000, v52
	v_lshlrev_b32_e32 v50, 16, v52
	v_mul_f32_e32 v51, v51, v51
	v_fmac_f32_e32 v51, v50, v50
	v_and_b32_e32 v56, 0xffff0000, v53
	v_add_f32_e32 v50, v64, v51
	v_lshlrev_b32_e32 v51, 16, v53
	v_mul_f32_e32 v56, v56, v56
	v_fmac_f32_e32 v56, v51, v51
	v_add_f32_e32 v50, v50, v56
	v_and_b32_e32 v56, 0xffff0000, v54
	v_lshlrev_b32_e32 v51, 16, v54
	v_mul_f32_e32 v56, v56, v56
	v_fmac_f32_e32 v56, v51, v51
	v_add_f32_e32 v50, v50, v56
	v_and_b32_e32 v56, 0xffff0000, v55
	v_lshlrev_b32_e32 v51, 16, v55
	v_mul_f32_e32 v56, v56, v56
	v_fmac_f32_e32 v56, v51, v51
	v_add_f32_e32 v50, v50, v56
	v_mov_b32_e32 v51, v50
	s_nop 1
	v_permlane16_swap_b32_e32 v51, v50
	s_waitcnt lgkmcnt(0)
	v_add_f32_e32 v50, v50, v51
	v_mov_b32_e32 v51, v50
	s_nop 1
	v_permlane32_swap_b32_e32 v51, v50
	s_and_saveexec_b64 s[10:11], s[0:1]
	s_cbranch_execz .LBB0_499
	s_waitcnt lgkmcnt(0)
	v_add_f32_e32 v50, v50, v51
	ds_write_b32 v236, v50
;     __device__ __forceinline__ void operator()(const f32x4 (&acc)[2][2][4][2], const pg8::Unit& u, int wr, int wc, int fr, int fq, LAS unsigned char* lds, int wid, int lane, const pg8::Unit& nxt, bool has_next, int ui) const {
;     ...
; #pragma unroll
;         for (int m = 0; m < 4; ++m) { RESNORM_ROWGROUP(0, m);
; #pragma unroll
;             for (int bj = 0; bj < 2; ++bj) xv[m][bj] = *(const v4u*)(X + (rowbase + rl0 + 128 + m * 16) * DM + col0 + bj * 128); }
; #pragma unroll
;         for (int m = 0; m < 4; ++m) RESNORM_ROWGROUP(1, m);
.LBB0_499:
	s_or_b64 exec, exec, s[10:11]
	v_lshl_add_u32 v50, v198, 2, s56
	ds_read_b32 v50, v50
	v_lshl_add_u64 v[52:53], s[30:31], 0, v[198:199]
	v_lshlrev_b64 v[52:53], 11, v[52:53]
	s_waitcnt lgkmcnt(0)
	v_pk_mul_f32 v[46:47], v[46:47], v[50:51] op_sel_hi:[1,0]
	v_pk_mul_f32 v[48:49], v[48:49], v[50:51] op_sel_hi:[1,0]
	v_pk_mul_f32 v[46:47], v[106:107], v[46:47]
	v_pk_mul_f32 v[44:45], v[44:45], v[50:51] op_sel_hi:[1,0]
	v_pk_mul_f32 v[42:43], v[42:43], v[50:51] op_sel_hi:[1,0]
	s_waitcnt vmcnt(11)
	v_lshlrev_b32_e32 v51, 16, v118
	v_add_f32_e32 v46, v46, v51
	v_and_b32_e32 v51, 0xffff0000, v118
	v_pk_mul_f32 v[48:49], v[108:109], v[48:49]
	v_add_f32_e32 v47, v47, v51
	v_lshlrev_b32_e32 v51, 16, v119
	v_add_f32_e32 v48, v48, v51
	v_and_b32_e32 v51, 0xffff0000, v119
	v_pk_mul_f32 v[42:43], v[98:99], v[42:43]
	v_add_f32_e32 v49, v49, v51
	v_lshlrev_b32_e32 v51, 16, v120
	v_add_f32_e32 v51, v42, v51
	v_and_b32_e32 v42, 0xffff0000, v120
	v_pk_mul_f32 v[44:45], v[100:101], v[44:45]
	v_add_f32_e32 v54, v43, v42
	v_lshlrev_b32_e32 v42, 16, v121
	v_add_f32_e32 v55, v44, v42
	v_and_b32_e32 v42, 0xffff0000, v121
	v_add_f32_e32 v45, v45, v42
	v_cvt_pk_bf16_f32 v42, v46, v47
	v_cvt_pk_bf16_f32 v43, v48, v49
	v_cvt_pk_bf16_f32 v44, v51, v54
	v_cvt_pk_bf16_f32 v45, v55, v45
	v_pk_mul_f32 v[38:39], v[38:39], v[50:51] op_sel_hi:[1,0]
	v_and_b32_e32 v47, 0xffff0000, v42
	v_lshlrev_b32_e32 v46, 16, v42
	v_mul_f32_e32 v47, v47, v47
	v_and_b32_e32 v48, 0xffff0000, v43
	v_fmac_f32_e32 v47, v46, v46
	v_lshlrev_b32_e32 v46, 16, v43
	v_mul_f32_e32 v48, v48, v48
	v_fmac_f32_e32 v48, v46, v46
	v_add_f32_e32 v46, v47, v48
	v_and_b32_e32 v48, 0xffff0000, v44
	v_lshlrev_b32_e32 v47, 16, v44
	v_mul_f32_e32 v48, v48, v48
	v_fmac_f32_e32 v48, v47, v47
	v_add_f32_e32 v46, v46, v48
	v_and_b32_e32 v48, 0xffff0000, v45
	v_lshlrev_b32_e32 v47, 16, v45
	v_mul_f32_e32 v48, v48, v48
	v_fmac_f32_e32 v48, v47, v47
	v_add_f32_e32 v48, v46, v48
	v_lshl_add_u64 v[46:47], s[36:37], 0, v[52:53]
	v_lshl_add_u64 v[46:47], v[208:209], 1, v[46:47]
	global_store_dwordx4 v[46:47], v[42:45], off
	v_pk_mul_f32 v[38:39], v[94:95], v[38:39]
	v_pk_mul_f32 v[40:41], v[40:41], v[50:51] op_sel_hi:[1,0]
	s_waitcnt vmcnt(11)
	v_lshlrev_b32_e32 v42, 16, v114
	v_add_f32_e32 v38, v38, v42
	v_and_b32_e32 v42, 0xffff0000, v114
	v_pk_mul_f32 v[40:41], v[96:97], v[40:41]
	v_add_f32_e32 v39, v39, v42
	v_lshlrev_b32_e32 v42, 16, v115
	v_pk_mul_f32 v[34:35], v[34:35], v[50:51] op_sel_hi:[1,0]
	v_add_f32_e32 v40, v40, v42
	v_and_b32_e32 v42, 0xffff0000, v115
	v_pk_mul_f32 v[34:35], v[90:91], v[34:35]
	v_add_f32_e32 v41, v41, v42
	v_lshlrev_b32_e32 v42, 16, v116
	v_pk_mul_f32 v[36:37], v[36:37], v[50:51] op_sel_hi:[1,0]
	v_add_f32_e32 v34, v34, v42
	v_and_b32_e32 v42, 0xffff0000, v116
	v_pk_mul_f32 v[36:37], v[92:93], v[36:37]
	v_add_f32_e32 v35, v35, v42
	v_lshlrev_b32_e32 v42, 16, v117
	v_add_f32_e32 v42, v36, v42
	v_and_b32_e32 v36, 0xffff0000, v117
	v_add_f32_e32 v43, v37, v36
	v_cvt_pk_bf16_f32 v36, v38, v39
	v_cvt_pk_bf16_f32 v37, v40, v41
	v_cvt_pk_bf16_f32 v38, v34, v35
	v_cvt_pk_bf16_f32 v39, v42, v43
	global_store_dwordx4 v[46:47], v[36:39], off offset:256
	v_and_b32_e32 v35, 0xffff0000, v36
	v_lshlrev_b32_e32 v34, 16, v36
	v_mul_f32_e32 v35, v35, v35
	v_fmac_f32_e32 v35, v34, v34
	v_and_b32_e32 v40, 0xffff0000, v37
	v_add_f32_e32 v34, v48, v35
	v_lshlrev_b32_e32 v35, 16, v37
	v_mul_f32_e32 v40, v40, v40
	v_fmac_f32_e32 v40, v35, v35
	v_add_f32_e32 v34, v34, v40
	v_and_b32_e32 v40, 0xffff0000, v38
	v_lshlrev_b32_e32 v35, 16, v38
	v_mul_f32_e32 v40, v40, v40
	v_fmac_f32_e32 v40, v35, v35
	v_add_f32_e32 v34, v34, v40
	v_and_b32_e32 v40, 0xffff0000, v39
	v_lshlrev_b32_e32 v35, 16, v39
	v_mul_f32_e32 v40, v40, v40
	v_fmac_f32_e32 v40, v35, v35
	v_add_f32_e32 v34, v34, v40
	v_mov_b32_e32 v35, v34
	s_nop 1
	v_permlane16_swap_b32_e32 v35, v34
	s_waitcnt lgkmcnt(0)
	v_add_f32_e32 v34, v34, v35
	v_mov_b32_e32 v35, v34
	s_nop 1
	v_permlane32_swap_b32_e32 v35, v34
	s_and_saveexec_b64 s[10:11], s[0:1]
	s_cbranch_execz .LBB0_501
	s_waitcnt lgkmcnt(0)
	v_add_f32_e32 v34, v34, v35
	ds_write_b32 v237, v34
.LBB0_501:
	s_or_b64 exec, exec, s[10:11]
	v_lshl_add_u32 v34, v200, 2, s56
	ds_read_b32 v34, v34
	v_lshl_add_u64 v[36:37], s[30:31], 0, v[200:201]
	v_lshlrev_b64 v[36:37], 11, v[36:37]
	s_waitcnt lgkmcnt(0)
	v_pk_mul_f32 v[30:31], v[30:31], v[34:35] op_sel_hi:[1,0]
	v_pk_mul_f32 v[32:33], v[32:33], v[34:35] op_sel_hi:[1,0]
	v_pk_mul_f32 v[30:31], v[106:107], v[30:31]
	v_pk_mul_f32 v[28:29], v[28:29], v[34:35] op_sel_hi:[1,0]
	v_pk_mul_f32 v[26:27], v[26:27], v[34:35] op_sel_hi:[1,0]
	s_waitcnt vmcnt(9)
	v_lshlrev_b32_e32 v35, 16, v86
	v_add_f32_e32 v30, v30, v35
	v_and_b32_e32 v35, 0xffff0000, v86
	v_pk_mul_f32 v[32:33], v[108:109], v[32:33]
	v_add_f32_e32 v31, v31, v35
	v_lshlrev_b32_e32 v35, 16, v87
	v_add_f32_e32 v32, v32, v35
	v_and_b32_e32 v35, 0xffff0000, v87
	v_pk_mul_f32 v[26:27], v[98:99], v[26:27]
	v_add_f32_e32 v33, v33, v35
	v_lshlrev_b32_e32 v35, 16, v88
	v_add_f32_e32 v35, v26, v35
	v_and_b32_e32 v26, 0xffff0000, v88
	v_pk_mul_f32 v[28:29], v[100:101], v[28:29]
	v_add_f32_e32 v38, v27, v26
	v_lshlrev_b32_e32 v26, 16, v89
	v_add_f32_e32 v39, v28, v26
	v_and_b32_e32 v26, 0xffff0000, v89
	v_add_f32_e32 v29, v29, v26
	v_cvt_pk_bf16_f32 v26, v30, v31
	v_cvt_pk_bf16_f32 v27, v32, v33
	v_cvt_pk_bf16_f32 v28, v35, v38
	v_cvt_pk_bf16_f32 v29, v39, v29
	v_pk_mul_f32 v[22:23], v[22:23], v[34:35] op_sel_hi:[1,0]
	v_and_b32_e32 v31, 0xffff0000, v26
	v_lshlrev_b32_e32 v30, 16, v26
	v_mul_f32_e32 v31, v31, v31
	v_and_b32_e32 v32, 0xffff0000, v27
	v_fmac_f32_e32 v31, v30, v30
	v_lshlrev_b32_e32 v30, 16, v27
	v_mul_f32_e32 v32, v32, v32
	v_fmac_f32_e32 v32, v30, v30
	v_add_f32_e32 v30, v31, v32
	v_and_b32_e32 v32, 0xffff0000, v28
	v_lshlrev_b32_e32 v31, 16, v28
	v_mul_f32_e32 v32, v32, v32
	v_fmac_f32_e32 v32, v31, v31
	v_add_f32_e32 v30, v30, v32
	v_and_b32_e32 v32, 0xffff0000, v29
	v_lshlrev_b32_e32 v31, 16, v29
	v_mul_f32_e32 v32, v32, v32
	v_fmac_f32_e32 v32, v31, v31
	v_add_f32_e32 v32, v30, v32
	v_lshl_add_u64 v[30:31], s[36:37], 0, v[36:37]
	v_lshl_add_u64 v[30:31], v[208:209], 1, v[30:31]
	global_store_dwordx4 v[30:31], v[26:29], off
	v_pk_mul_f32 v[22:23], v[94:95], v[22:23]
	v_pk_mul_f32 v[24:25], v[24:25], v[34:35] op_sel_hi:[1,0]
	s_waitcnt vmcnt(9)
;     __device__ __forceinline__ void operator()(const f32x4 (&acc)[2][2][4][2], const pg8::Unit& u, int wr, int wc, int fr, int fq, LAS unsigned char* lds, int wid, int lane, const pg8::Unit& nxt, bool has_next, int ui) const {
;     ...
; #pragma unroll
;         for (int m = 0; m < 4; ++m) { RESNORM_ROWGROUP(0, m);
; #pragma unroll
;             for (int bj = 0; bj < 2; ++bj) xv[m][bj] = *(const v4u*)(X + (rowbase + rl0 + 128 + m * 16) * DM + col0 + bj * 128); }
; #pragma unroll
;         for (int m = 0; m < 4; ++m) RESNORM_ROWGROUP(1, m);
	v_lshlrev_b32_e32 v26, 16, v82
	v_add_f32_e32 v22, v22, v26
	v_and_b32_e32 v26, 0xffff0000, v82
	v_pk_mul_f32 v[24:25], v[96:97], v[24:25]
	v_add_f32_e32 v23, v23, v26
	v_lshlrev_b32_e32 v26, 16, v83
	v_pk_mul_f32 v[18:19], v[18:19], v[34:35] op_sel_hi:[1,0]
	v_add_f32_e32 v24, v24, v26
	v_and_b32_e32 v26, 0xffff0000, v83
	v_pk_mul_f32 v[18:19], v[90:91], v[18:19]
	v_add_f32_e32 v25, v25, v26
	v_lshlrev_b32_e32 v26, 16, v84
	v_pk_mul_f32 v[20:21], v[20:21], v[34:35] op_sel_hi:[1,0]
	v_add_f32_e32 v18, v18, v26
	v_and_b32_e32 v26, 0xffff0000, v84
	v_pk_mul_f32 v[20:21], v[92:93], v[20:21]
	v_add_f32_e32 v19, v19, v26
	v_lshlrev_b32_e32 v26, 16, v85
	v_add_f32_e32 v26, v20, v26
	v_and_b32_e32 v20, 0xffff0000, v85
	v_add_f32_e32 v27, v21, v20
	v_cvt_pk_bf16_f32 v20, v22, v23
	v_cvt_pk_bf16_f32 v21, v24, v25
	v_cvt_pk_bf16_f32 v22, v18, v19
	v_cvt_pk_bf16_f32 v23, v26, v27
	global_store_dwordx4 v[30:31], v[20:23], off offset:256
	v_and_b32_e32 v19, 0xffff0000, v20
	v_lshlrev_b32_e32 v18, 16, v20
	v_mul_f32_e32 v19, v19, v19
	v_fmac_f32_e32 v19, v18, v18
	v_and_b32_e32 v24, 0xffff0000, v21
	v_add_f32_e32 v18, v32, v19
	v_lshlrev_b32_e32 v19, 16, v21
	v_mul_f32_e32 v24, v24, v24
	v_fmac_f32_e32 v24, v19, v19
	v_add_f32_e32 v18, v18, v24
	v_and_b32_e32 v24, 0xffff0000, v22
	v_lshlrev_b32_e32 v19, 16, v22
	v_mul_f32_e32 v24, v24, v24
	v_fmac_f32_e32 v24, v19, v19
	v_add_f32_e32 v18, v18, v24
	v_and_b32_e32 v24, 0xffff0000, v23
	v_lshlrev_b32_e32 v19, 16, v23
	v_mul_f32_e32 v24, v24, v24
	v_fmac_f32_e32 v24, v19, v19
	v_add_f32_e32 v18, v18, v24
	v_mov_b32_e32 v19, v18
	s_nop 1
	v_permlane16_swap_b32_e32 v19, v18
	s_waitcnt lgkmcnt(0)
	v_add_f32_e32 v18, v18, v19
	v_mov_b32_e32 v19, v18
	s_nop 1
	v_permlane32_swap_b32_e32 v19, v18
	s_and_saveexec_b64 s[10:11], s[0:1]
	s_cbranch_execz .LBB0_503
	s_waitcnt lgkmcnt(0)
	v_add_f32_e32 v18, v18, v19
	ds_write_b32 v238, v18
.LBB0_503:
	s_or_b64 exec, exec, s[10:11]
	v_lshl_add_u32 v18, v202, 2, s56
	ds_read_b32 v18, v18
	v_lshl_add_u64 v[20:21], s[30:31], 0, v[202:203]
	v_lshlrev_b64 v[20:21], 11, v[20:21]
	s_waitcnt lgkmcnt(0)
	v_pk_mul_f32 v[14:15], v[14:15], v[18:19] op_sel_hi:[1,0]
	v_pk_mul_f32 v[16:17], v[16:17], v[18:19] op_sel_hi:[1,0]
	v_pk_mul_f32 v[14:15], v[106:107], v[14:15]
	v_pk_mul_f32 v[12:13], v[12:13], v[18:19] op_sel_hi:[1,0]
	v_pk_mul_f32 v[10:11], v[10:11], v[18:19] op_sel_hi:[1,0]
	s_waitcnt vmcnt(7)
	v_lshlrev_b32_e32 v19, 16, v70
	v_add_f32_e32 v14, v14, v19
	v_and_b32_e32 v19, 0xffff0000, v70
	v_pk_mul_f32 v[16:17], v[108:109], v[16:17]
	v_add_f32_e32 v15, v15, v19
	v_lshlrev_b32_e32 v19, 16, v71
	v_add_f32_e32 v16, v16, v19
	v_and_b32_e32 v19, 0xffff0000, v71
	v_pk_mul_f32 v[10:11], v[98:99], v[10:11]
	v_add_f32_e32 v17, v17, v19
	v_lshlrev_b32_e32 v19, 16, v72
	v_add_f32_e32 v19, v10, v19
	v_and_b32_e32 v10, 0xffff0000, v72
	v_pk_mul_f32 v[12:13], v[100:101], v[12:13]
	v_add_f32_e32 v22, v11, v10
	v_lshlrev_b32_e32 v10, 16, v73
	v_add_f32_e32 v23, v12, v10
	v_and_b32_e32 v10, 0xffff0000, v73
	v_add_f32_e32 v13, v13, v10
	v_cvt_pk_bf16_f32 v10, v14, v15
	v_cvt_pk_bf16_f32 v11, v16, v17
	v_cvt_pk_bf16_f32 v12, v19, v22
	v_cvt_pk_bf16_f32 v13, v23, v13
	v_pk_mul_f32 v[6:7], v[6:7], v[18:19] op_sel_hi:[1,0]
	v_and_b32_e32 v15, 0xffff0000, v10
	v_lshlrev_b32_e32 v14, 16, v10
	v_mul_f32_e32 v15, v15, v15
	v_and_b32_e32 v16, 0xffff0000, v11
	v_fmac_f32_e32 v15, v14, v14
	v_lshlrev_b32_e32 v14, 16, v11
	v_mul_f32_e32 v16, v16, v16
	v_fmac_f32_e32 v16, v14, v14
	v_add_f32_e32 v14, v15, v16
	v_and_b32_e32 v16, 0xffff0000, v12
	v_lshlrev_b32_e32 v15, 16, v12
	v_mul_f32_e32 v16, v16, v16
	v_fmac_f32_e32 v16, v15, v15
	v_add_f32_e32 v14, v14, v16
	v_and_b32_e32 v16, 0xffff0000, v13
	v_lshlrev_b32_e32 v15, 16, v13
	v_mul_f32_e32 v16, v16, v16
	v_fmac_f32_e32 v16, v15, v15
	v_add_f32_e32 v16, v14, v16
	v_lshl_add_u64 v[14:15], s[36:37], 0, v[20:21]
	v_lshl_add_u64 v[14:15], v[208:209], 1, v[14:15]
	global_store_dwordx4 v[14:15], v[10:13], off
	v_pk_mul_f32 v[6:7], v[94:95], v[6:7]
	v_pk_mul_f32 v[8:9], v[8:9], v[18:19] op_sel_hi:[1,0]
	s_waitcnt vmcnt(7)
	v_lshlrev_b32_e32 v10, 16, v66
	v_add_f32_e32 v6, v6, v10
	v_and_b32_e32 v10, 0xffff0000, v66
	v_pk_mul_f32 v[8:9], v[96:97], v[8:9]
	v_add_f32_e32 v7, v7, v10
	v_lshlrev_b32_e32 v10, 16, v67
	v_pk_mul_f32 v[2:3], v[2:3], v[18:19] op_sel_hi:[1,0]
	v_add_f32_e32 v8, v8, v10
	v_and_b32_e32 v10, 0xffff0000, v67
	v_pk_mul_f32 v[2:3], v[90:91], v[2:3]
	v_add_f32_e32 v9, v9, v10
	v_lshlrev_b32_e32 v10, 16, v68
	v_pk_mul_f32 v[4:5], v[4:5], v[18:19] op_sel_hi:[1,0]
	v_add_f32_e32 v2, v2, v10
	v_and_b32_e32 v10, 0xffff0000, v68
	v_pk_mul_f32 v[4:5], v[92:93], v[4:5]
	v_add_f32_e32 v3, v3, v10
	v_lshlrev_b32_e32 v10, 16, v69
	v_add_f32_e32 v10, v4, v10
	v_and_b32_e32 v4, 0xffff0000, v69
	v_add_f32_e32 v11, v5, v4
	v_cvt_pk_bf16_f32 v4, v6, v7
	v_cvt_pk_bf16_f32 v5, v8, v9
	v_cvt_pk_bf16_f32 v6, v2, v3
	v_cvt_pk_bf16_f32 v7, v10, v11
	global_store_dwordx4 v[14:15], v[4:7], off offset:256
	v_and_b32_e32 v3, 0xffff0000, v4
	v_lshlrev_b32_e32 v2, 16, v4
	v_mul_f32_e32 v3, v3, v3
	v_fmac_f32_e32 v3, v2, v2
	v_and_b32_e32 v8, 0xffff0000, v5
	v_add_f32_e32 v2, v16, v3
	v_lshlrev_b32_e32 v3, 16, v5
	v_mul_f32_e32 v8, v8, v8
	v_fmac_f32_e32 v8, v3, v3
	v_add_f32_e32 v2, v2, v8
	v_and_b32_e32 v8, 0xffff0000, v6
	v_lshlrev_b32_e32 v3, 16, v6
	v_mul_f32_e32 v8, v8, v8
	v_fmac_f32_e32 v8, v3, v3
	v_add_f32_e32 v2, v2, v8
	v_and_b32_e32 v8, 0xffff0000, v7
	v_lshlrev_b32_e32 v3, 16, v7
	v_mul_f32_e32 v8, v8, v8
	v_fmac_f32_e32 v8, v3, v3
	v_add_f32_e32 v2, v2, v8
	v_mov_b32_e32 v3, v2
	s_nop 1
	v_permlane16_swap_b32_e32 v3, v2
	s_waitcnt lgkmcnt(0)
	v_add_f32_e32 v2, v2, v3
	v_mov_b32_e32 v3, v2
	s_nop 1
	v_permlane32_swap_b32_e32 v3, v2
	s_and_saveexec_b64 s[10:11], s[0:1]
	s_cbranch_execz .LBB0_505
	s_waitcnt lgkmcnt(0)
	v_add_f32_e32 v2, v2, v3
	ds_write_b32 v239, v2

;     __device__ __forceinline__ void operator()(const f32x4 (&acc)[2][2][4][2], const pg8::Unit& u, int wr, int wc, int fr, int fq, LAS unsigned char* lds, int wid, int lane, const pg8::Unit& nxt, bool has_next, int ui) const {
;     ...
;         v4u xv[4][2];
; #pragma unroll
;         for (int m = 0; m < 4; ++m)
; #pragma unroll
;             for (int bj = 0; bj < 2; ++bj) xv[m][bj] = *(const v4u*)(X + (rowbase + rl0 + m * 16) * DM + col0 + bj * 128);
;         f32x4 gv[2][2];
; #pragma unroll
;         for (int bj = 0; bj < 2; ++bj)
; #pragma unroll
;             for (int n = 0; n < 2; ++n) gv[bj][n] = *(const f32x4*)(gpost + col0 + bj * 128 + 4 * n);
; #pragma unroll
;         for (int ai = 0; ai < 2; ++ai)
; #pragma unroll
;             for (int m = 0; m < 4; ++m) { float ss = 0.f;
; #pragma unroll
;                 for (int bj = 0; bj < 2; ++bj)
; #pragma unroll
;                     for (int n = 0; n < 2; ++n) { const f32x4 v = acc[ai][bj][m][n]; ss += (v[0] * v[0] + v[1] * v[1]) + (v[2] * v[2] + v[3] * v[3]); }
;                 ss += __shfl_xor(ss, 16); ss += __shfl_xor(ss, 32);
;                 if (fq == 0) P[(rl0 + ai * 128 + m * 16) * 4 + wc] = ss; }
.LBB0_670:
	s_ashr_i32 s25, s24, 31
	v_lshl_or_b32 v208, s18, 8, v228
	s_lshl_b64 s[24:25], s[24:25], 8
	v_lshl_add_u64 v[90:91], s[24:25], 0, v[186:187]
	v_ashrrev_i32_e32 v209, 31, v208
	v_lshl_add_u64 v[92:93], v[208:209], 1, s[36:37]
	v_lshlrev_b64 v[216:217], 11, v[90:91]
	v_lshl_add_u64 v[90:91], v[92:93], 0, v[216:217]
	v_add_co_u32_e32 v92, vcc, 0x8000, v90
	s_mov_b32 s10, 0x10000
	s_nop 0
	v_addc_co_u32_e32 v93, vcc, 0, v91, vcc
	global_load_dwordx4 v[174:177], v[90:91], off
	global_load_dwordx4 v[170:173], v[90:91], off offset:256
	global_load_dwordx4 v[166:169], v[92:93], off
	global_load_dwordx4 v[162:165], v[92:93], off offset:256
	v_add_co_u32_e32 v92, vcc, s10, v90
	s_mov_b32 s10, 0x18000
	s_nop 0
	v_addc_co_u32_e32 v93, vcc, 0, v91, vcc
	v_add_co_u32_e32 v90, vcc, s10, v90
	v_lshl_add_u64 v[94:95], v[208:209], 2, s[14:15]
	s_nop 0
	v_addc_co_u32_e32 v91, vcc, 0, v91, vcc
	global_load_dwordx4 v[158:161], v[92:93], off
	global_load_dwordx4 v[154:157], v[92:93], off offset:256
	global_load_dwordx4 v[150:153], v[90:91], off
	global_load_dwordx4 v[146:149], v[90:91], off offset:256
	global_load_dwordx4 v[98:101], v[94:95], off offset:16
	global_load_dwordx4 v[106:109], v[94:95], off
	s_nop 0
	global_load_dwordx4 v[90:93], v[94:95], off offset:528
	s_nop 0
	global_load_dwordx4 v[94:97], v[94:95], off offset:512
	v_and_b32_e32 v211, 64, v249
	v_xor_b32_e32 v210, 16, v249
	v_add_u32_e32 v211, 64, v211
	v_cmp_lt_i32_e32 vcc, v210, v211
	v_mul_f32_e32 v212, v145, v145
	v_fmac_f32_e32 v212, v144, v144
	v_cndmask_b32_e32 v210, v249, v210, vcc
	v_lshlrev_b32_e32 v241, 2, v210
	v_mul_f32_e32 v210, v143, v143
	v_fmac_f32_e32 v210, v142, v142
	v_add_f32_e32 v210, v210, v212
	v_mul_f32_e32 v212, v139, v139
	v_mul_f32_e32 v213, v141, v141
	v_fmac_f32_e32 v212, v138, v138
	v_fmac_f32_e32 v213, v140, v140
	v_add_f32_e32 v212, v212, v213
	v_add_f32_e32 v210, v210, v212
	v_mul_f32_e32 v212, v135, v135
	v_mul_f32_e32 v213, v137, v137
	v_fmac_f32_e32 v212, v134, v134
	v_fmac_f32_e32 v213, v136, v136
	v_add_f32_e32 v212, v212, v213
	v_add_f32_e32 v210, v210, v212
	v_mul_f32_e32 v212, v131, v131
	v_mul_f32_e32 v213, v133, v133
	v_fmac_f32_e32 v212, v130, v130
	v_fmac_f32_e32 v213, v132, v132
	v_add_f32_e32 v212, v212, v213
	v_add_f32_e32 v210, v210, v212
	v_mov_b32_e32 v212, v210
	s_nop 1
	v_permlane16_swap_b32_e32 v212, v210
	v_xor_b32_e32 v213, 32, v249
	v_cmp_lt_i32_e32 vcc, v213, v211
	s_waitcnt lgkmcnt(0)
	v_add_f32_e32 v214, v210, v212
	v_cndmask_b32_e32 v211, v249, v213, vcc
	v_lshlrev_b32_e32 v242, 2, v211
	v_mov_b32_e32 v215, v214
	s_nop 1
	v_permlane32_swap_b32_e32 v215, v214
	s_and_saveexec_b64 s[10:11], s[0:1]
	s_cbranch_execz .LBB0_672
	s_waitcnt lgkmcnt(0)
	v_add_f32_e32 v210, v214, v215
	ds_write_b32 v230, v210

;     __device__ __forceinline__ void operator()(const f32x4 (&acc)[2][2][4][2], const pg8::Unit& u, int wr, int wc, int fr, int fq, LAS unsigned char* lds, int wid, int lane, const pg8::Unit& nxt, bool has_next, int ui) const {
;     ...
;         asm volatile("s_waitcnt lgkmcnt(0)" ::: "memory"); __builtin_amdgcn_s_barrier(); asm volatile("" ::: "memory");
;     ...
; #pragma unroll
;         for (int m = 0; m < 4; ++m) { RESNORM_ROWGROUP(0, m);
.LBB0_692:
	s_or_b64 exec, exec, s[26:27]
	s_waitcnt lgkmcnt(0)
	s_barrier
	ds_read_b32 v210, v231
	s_waitcnt lgkmcnt(0)
	v_pk_mul_f32 v[142:143], v[142:143], v[210:211] op_sel_hi:[1,0]
	v_pk_mul_f32 v[144:145], v[144:145], v[210:211] op_sel_hi:[1,0]
	s_waitcnt vmcnt(0)
	v_pk_mul_f32 v[142:143], v[106:107], v[142:143]
	v_pk_mul_f32 v[140:141], v[140:141], v[210:211] op_sel_hi:[1,0]
	v_pk_mul_f32 v[138:139], v[138:139], v[210:211] op_sel_hi:[1,0]
	v_lshlrev_b32_e32 v211, 16, v174
	v_and_b32_e32 v174, 0xffff0000, v174
	v_pk_mul_f32 v[144:145], v[108:109], v[144:145]
	v_add_f32_e32 v143, v143, v174
	v_lshlrev_b32_e32 v174, 16, v175
	v_add_f32_e32 v144, v144, v174
	v_and_b32_e32 v174, 0xffff0000, v175
	v_pk_mul_f32 v[138:139], v[98:99], v[138:139]
	v_add_f32_e32 v145, v145, v174
	v_lshlrev_b32_e32 v174, 16, v176
	v_add_f32_e32 v138, v138, v174
	v_and_b32_e32 v174, 0xffff0000, v176
	v_pk_mul_f32 v[140:141], v[100:101], v[140:141]
	v_add_f32_e32 v139, v139, v174
	v_lshlrev_b32_e32 v174, 16, v177
	v_add_f32_e32 v142, v142, v211
	v_add_f32_e32 v174, v140, v174
	v_and_b32_e32 v140, 0xffff0000, v177
	v_add_f32_e32 v175, v141, v140
	v_cvt_pk_bf16_f32 v140, v142, v143
	v_cvt_pk_bf16_f32 v141, v144, v145
	v_cvt_pk_bf16_f32 v142, v138, v139
	v_cvt_pk_bf16_f32 v143, v174, v175
	v_pk_mul_f32 v[134:135], v[134:135], v[210:211] op_sel_hi:[1,0]
	v_and_b32_e32 v139, 0xffff0000, v140
	v_lshlrev_b32_e32 v138, 16, v140
	v_mul_f32_e32 v139, v139, v139
	v_and_b32_e32 v144, 0xffff0000, v141
	v_fmac_f32_e32 v139, v138, v138
	v_lshlrev_b32_e32 v138, 16, v141
	v_mul_f32_e32 v144, v144, v144
	v_fmac_f32_e32 v144, v138, v138
	v_add_f32_e32 v138, v139, v144
	v_and_b32_e32 v144, 0xffff0000, v142
	v_lshlrev_b32_e32 v139, 16, v142
	v_mul_f32_e32 v144, v144, v144
	v_fmac_f32_e32 v144, v139, v139
	v_add_f32_e32 v138, v138, v144
	v_and_b32_e32 v144, 0xffff0000, v143
	v_lshlrev_b32_e32 v139, 16, v143
	v_mul_f32_e32 v144, v144, v144
	v_fmac_f32_e32 v144, v139, v139
	v_add_f32_e32 v174, v138, v144
	v_lshl_add_u64 v[138:139], s[36:37], 0, v[216:217]
	v_lshl_add_u64 v[144:145], v[208:209], 1, v[138:139]
	global_store_dwordx4 v[144:145], v[140:143], off
	v_pk_mul_f32 v[134:135], v[94:95], v[134:135]
	v_pk_mul_f32 v[136:137], v[136:137], v[210:211] op_sel_hi:[1,0]
	v_lshlrev_b32_e32 v140, 16, v170
	v_add_f32_e32 v134, v134, v140
	v_and_b32_e32 v140, 0xffff0000, v170
	v_pk_mul_f32 v[136:137], v[96:97], v[136:137]
	v_add_f32_e32 v135, v135, v140
	v_lshlrev_b32_e32 v140, 16, v171
	v_pk_mul_f32 v[130:131], v[130:131], v[210:211] op_sel_hi:[1,0]
	v_add_f32_e32 v136, v136, v140
	v_and_b32_e32 v140, 0xffff0000, v171
	v_pk_mul_f32 v[130:131], v[90:91], v[130:131]
	v_add_f32_e32 v137, v137, v140
	v_lshlrev_b32_e32 v140, 16, v172
	v_pk_mul_f32 v[132:133], v[132:133], v[210:211] op_sel_hi:[1,0]
	v_add_f32_e32 v130, v130, v140
	v_and_b32_e32 v140, 0xffff0000, v172
	v_pk_mul_f32 v[132:133], v[92:93], v[132:133]
	v_add_f32_e32 v131, v131, v140
	v_lshlrev_b32_e32 v140, 16, v173
	v_add_f32_e32 v140, v132, v140
	v_and_b32_e32 v132, 0xffff0000, v173
	v_add_f32_e32 v141, v133, v132
	v_cvt_pk_bf16_f32 v132, v134, v135
	v_cvt_pk_bf16_f32 v133, v136, v137
	v_cvt_pk_bf16_f32 v134, v130, v131
	v_cvt_pk_bf16_f32 v135, v140, v141
	global_store_dwordx4 v[144:145], v[132:135], off offset:256
	v_and_b32_e32 v131, 0xffff0000, v132
	v_lshlrev_b32_e32 v130, 16, v132
	v_mul_f32_e32 v131, v131, v131
	v_fmac_f32_e32 v131, v130, v130
	v_and_b32_e32 v136, 0xffff0000, v133
	v_add_f32_e32 v130, v174, v131
	v_lshlrev_b32_e32 v131, 16, v133
	v_mul_f32_e32 v136, v136, v136
	v_fmac_f32_e32 v136, v131, v131
	v_add_f32_e32 v130, v130, v136
	v_and_b32_e32 v136, 0xffff0000, v134
	v_lshlrev_b32_e32 v131, 16, v134
	v_mul_f32_e32 v136, v136, v136
	v_fmac_f32_e32 v136, v131, v131
	v_add_f32_e32 v130, v130, v136
	v_and_b32_e32 v136, 0xffff0000, v135
	v_lshlrev_b32_e32 v131, 16, v135
	v_mul_f32_e32 v136, v136, v136
	v_fmac_f32_e32 v136, v131, v131
	v_add_f32_e32 v130, v130, v136
	v_mov_b32_e32 v131, v130
	s_nop 1
	v_permlane16_swap_b32_e32 v131, v130
	s_waitcnt lgkmcnt(0)
	v_add_f32_e32 v130, v130, v131
	v_mov_b32_e32 v131, v130
	s_nop 1
	v_permlane32_swap_b32_e32 v131, v130
	s_and_saveexec_b64 s[10:11], s[0:1]
	s_cbranch_execz .LBB0_694
	s_waitcnt lgkmcnt(0)
	v_add_f32_e32 v130, v130, v131
	v_add_u32_e32 v131, s12, v229
	ds_write_b32 v131, v130
;     __device__ __forceinline__ void operator()(const f32x4 (&acc)[2][2][4][2], const pg8::Unit& u, int wr, int wc, int fr, int fq, LAS unsigned char* lds, int wid, int lane, const pg8::Unit& nxt, bool has_next, int ui) const {
;     ...
; #pragma unroll
;         for (int m = 0; m < 4; ++m) { RESNORM_ROWGROUP(0, m);
; #pragma unroll
;             for (int bj = 0; bj < 2; ++bj) xv[m][bj] = *(const v4u*)(X + (rowbase + rl0 + 128 + m * 16) * DM + col0 + bj * 128); }
.LBB0_694:
	s_or_b64 exec, exec, s[10:11]
	s_mov_b64 s[10:11], 0x40000
	s_waitcnt lgkmcnt(0)
	v_lshl_add_u64 v[130:131], v[138:139], 0, s[10:11]
	v_lshlrev_b64 v[138:139], 1, v[208:209]
	v_lshl_add_u64 v[140:141], v[130:131], 0, v[138:139]
	v_lshl_add_u32 v130, v190, 2, s56
	ds_read_b32 v142, v130
	global_load_dwordx4 v[134:137], v[140:141], off
	global_load_dwordx4 v[130:133], v[140:141], off offset:256
	v_lshl_add_u64 v[144:145], s[24:25], 0, v[190:191]
	v_lshlrev_b64 v[144:145], 11, v[144:145]
	s_waitcnt lgkmcnt(0)
	v_pk_mul_f32 v[126:127], v[126:127], v[142:143] op_sel_hi:[1,0]
	v_pk_mul_f32 v[128:129], v[128:129], v[142:143] op_sel_hi:[1,0]
	v_pk_mul_f32 v[126:127], v[106:107], v[126:127]
	v_pk_mul_f32 v[124:125], v[124:125], v[142:143] op_sel_hi:[1,0]
	v_pk_mul_f32 v[122:123], v[122:123], v[142:143] op_sel_hi:[1,0]
	v_lshlrev_b32_e32 v143, 16, v166
	v_add_f32_e32 v126, v126, v143
	v_and_b32_e32 v143, 0xffff0000, v166
	v_pk_mul_f32 v[128:129], v[108:109], v[128:129]
	v_add_f32_e32 v127, v127, v143
	v_lshlrev_b32_e32 v143, 16, v167
	v_add_f32_e32 v128, v128, v143
	v_and_b32_e32 v143, 0xffff0000, v167
	v_pk_mul_f32 v[122:123], v[98:99], v[122:123]
	v_add_f32_e32 v129, v129, v143
	v_lshlrev_b32_e32 v143, 16, v168
	v_add_f32_e32 v143, v122, v143
	v_and_b32_e32 v122, 0xffff0000, v168
	v_pk_mul_f32 v[124:125], v[100:101], v[124:125]
	v_add_f32_e32 v166, v123, v122
	v_lshlrev_b32_e32 v122, 16, v169
	v_add_f32_e32 v167, v124, v122
	v_and_b32_e32 v122, 0xffff0000, v169
	v_add_f32_e32 v125, v125, v122
	v_cvt_pk_bf16_f32 v122, v126, v127
	v_cvt_pk_bf16_f32 v123, v128, v129
	v_cvt_pk_bf16_f32 v124, v143, v166
	v_cvt_pk_bf16_f32 v125, v167, v125
	v_pk_mul_f32 v[118:119], v[118:119], v[142:143] op_sel_hi:[1,0]
	v_and_b32_e32 v127, 0xffff0000, v122
	v_lshlrev_b32_e32 v126, 16, v122
	v_mul_f32_e32 v127, v127, v127
	v_and_b32_e32 v128, 0xffff0000, v123
	v_fmac_f32_e32 v127, v126, v126
	v_lshlrev_b32_e32 v126, 16, v123
	v_mul_f32_e32 v128, v128, v128
	v_fmac_f32_e32 v128, v126, v126
	v_add_f32_e32 v126, v127, v128
	v_and_b32_e32 v128, 0xffff0000, v124
	v_lshlrev_b32_e32 v127, 16, v124
	v_mul_f32_e32 v128, v128, v128
	v_fmac_f32_e32 v128, v127, v127
	v_add_f32_e32 v126, v126, v128
	v_and_b32_e32 v128, 0xffff0000, v125
	v_lshlrev_b32_e32 v127, 16, v125
	v_mul_f32_e32 v128, v128, v128
	v_fmac_f32_e32 v128, v127, v127
	v_add_f32_e32 v128, v126, v128
	v_lshl_add_u64 v[126:127], s[36:37], 0, v[144:145]
	v_lshl_add_u64 v[126:127], v[126:127], 0, v[138:139]
	global_store_dwordx4 v[126:127], v[122:125], off
	v_pk_mul_f32 v[118:119], v[94:95], v[118:119]
	v_pk_mul_f32 v[120:121], v[120:121], v[142:143] op_sel_hi:[1,0]
	v_lshlrev_b32_e32 v122, 16, v162
	v_add_f32_e32 v118, v118, v122
	v_and_b32_e32 v122, 0xffff0000, v162
	v_pk_mul_f32 v[120:121], v[96:97], v[120:121]
	v_add_f32_e32 v119, v119, v122
	v_lshlrev_b32_e32 v122, 16, v163
	v_pk_mul_f32 v[114:115], v[114:115], v[142:143] op_sel_hi:[1,0]
	v_add_f32_e32 v120, v120, v122
	v_and_b32_e32 v122, 0xffff0000, v163
	v_pk_mul_f32 v[114:115], v[90:91], v[114:115]
	v_add_f32_e32 v121, v121, v122
	v_lshlrev_b32_e32 v122, 16, v164
	v_pk_mul_f32 v[116:117], v[116:117], v[142:143] op_sel_hi:[1,0]
	v_add_f32_e32 v114, v114, v122
	v_and_b32_e32 v122, 0xffff0000, v164
	v_pk_mul_f32 v[116:117], v[92:93], v[116:117]
	v_add_f32_e32 v115, v115, v122
	v_lshlrev_b32_e32 v122, 16, v165
	v_add_f32_e32 v122, v116, v122
	v_and_b32_e32 v116, 0xffff0000, v165
	v_add_f32_e32 v123, v117, v116
	v_cvt_pk_bf16_f32 v116, v118, v119
	v_cvt_pk_bf16_f32 v117, v120, v121
	v_cvt_pk_bf16_f32 v118, v114, v115
	v_cvt_pk_bf16_f32 v119, v122, v123
	global_store_dwordx4 v[126:127], v[116:119], off offset:256
	v_and_b32_e32 v115, 0xffff0000, v116
	v_lshlrev_b32_e32 v114, 16, v116
	v_mul_f32_e32 v115, v115, v115
	v_fmac_f32_e32 v115, v114, v114
	v_and_b32_e32 v120, 0xffff0000, v117
	v_add_f32_e32 v114, v128, v115
	v_lshlrev_b32_e32 v115, 16, v117
	v_mul_f32_e32 v120, v120, v120
	v_fmac_f32_e32 v120, v115, v115
	v_add_f32_e32 v114, v114, v120
	v_and_b32_e32 v120, 0xffff0000, v118
	v_lshlrev_b32_e32 v115, 16, v118
	v_mul_f32_e32 v120, v120, v120
	v_fmac_f32_e32 v120, v115, v115
	v_add_f32_e32 v114, v114, v120
	v_and_b32_e32 v120, 0xffff0000, v119
	v_lshlrev_b32_e32 v115, 16, v119
	v_mul_f32_e32 v120, v120, v120
	v_fmac_f32_e32 v120, v115, v115
	v_add_f32_e32 v114, v114, v120
	v_mov_b32_e32 v115, v114
	s_nop 1
	v_permlane16_swap_b32_e32 v115, v114
	s_waitcnt lgkmcnt(0)
	v_add_f32_e32 v114, v114, v115
	v_mov_b32_e32 v115, v114
	s_nop 1
	v_permlane32_swap_b32_e32 v115, v114
	s_and_saveexec_b64 s[10:11], s[0:1]
	s_cbranch_execz .LBB0_696
	s_waitcnt lgkmcnt(0)
	v_add_f32_e32 v114, v114, v115
	ds_write_b32 v233, v114
;     __device__ __forceinline__ void operator()(const f32x4 (&acc)[2][2][4][2], const pg8::Unit& u, int wr, int wc, int fr, int fq, LAS unsigned char* lds, int wid, int lane, const pg8::Unit& nxt, bool has_next, int ui) const {
;     ...
; #pragma unroll
;         for (int m = 0; m < 4; ++m) { RESNORM_ROWGROUP(0, m);
; #pragma unroll
;             for (int bj = 0; bj < 2; ++bj) xv[m][bj] = *(const v4u*)(X + (rowbase + rl0 + 128 + m * 16) * DM + col0 + bj * 128); }
.LBB0_696:
	s_or_b64 exec, exec, s[10:11]
	s_mov_b64 s[10:11], 0x8000
	v_add_co_u32_e32 v116, vcc, 0x8000, v140
	s_waitcnt lgkmcnt(0)
	v_lshl_add_u64 v[114:115], v[140:141], 0, s[10:11]
	v_addc_co_u32_e32 v117, vcc, 0, v141, vcc
	v_lshl_add_u32 v118, v192, 2, s56
	ds_read_b32 v122, v118
	global_load_dwordx4 v[118:121], v[116:117], off
	s_nop 0
	global_load_dwordx4 v[114:117], v[114:115], off offset:256
	v_lshl_add_u64 v[124:125], s[24:25], 0, v[192:193]
	v_lshlrev_b64 v[124:125], 11, v[124:125]
	s_waitcnt lgkmcnt(0)
	v_pk_mul_f32 v[110:111], v[110:111], v[122:123] op_sel_hi:[1,0]
	v_pk_mul_f32 v[112:113], v[112:113], v[122:123] op_sel_hi:[1,0]
	v_pk_mul_f32 v[110:111], v[106:107], v[110:111]
	v_pk_mul_f32 v[104:105], v[104:105], v[122:123] op_sel_hi:[1,0]
	v_pk_mul_f32 v[102:103], v[102:103], v[122:123] op_sel_hi:[1,0]
	v_lshlrev_b32_e32 v123, 16, v158
	v_add_f32_e32 v110, v110, v123
	v_and_b32_e32 v123, 0xffff0000, v158
	v_pk_mul_f32 v[112:113], v[108:109], v[112:113]
	v_add_f32_e32 v111, v111, v123
	v_lshlrev_b32_e32 v123, 16, v159
	v_add_f32_e32 v112, v112, v123
	v_and_b32_e32 v123, 0xffff0000, v159
	v_pk_mul_f32 v[102:103], v[98:99], v[102:103]
	v_add_f32_e32 v113, v113, v123
	v_lshlrev_b32_e32 v123, 16, v160
	v_add_f32_e32 v123, v102, v123
	v_and_b32_e32 v102, 0xffff0000, v160
	v_pk_mul_f32 v[104:105], v[100:101], v[104:105]
	v_add_f32_e32 v126, v103, v102
	v_lshlrev_b32_e32 v102, 16, v161
	v_add_f32_e32 v127, v104, v102
	v_and_b32_e32 v102, 0xffff0000, v161
	v_add_f32_e32 v105, v105, v102
	v_cvt_pk_bf16_f32 v102, v110, v111
	v_cvt_pk_bf16_f32 v103, v112, v113
	v_cvt_pk_bf16_f32 v104, v123, v126
	v_cvt_pk_bf16_f32 v105, v127, v105
	v_pk_mul_f32 v[86:87], v[86:87], v[122:123] op_sel_hi:[1,0]
	v_and_b32_e32 v111, 0xffff0000, v102
	v_lshlrev_b32_e32 v110, 16, v102
	v_mul_f32_e32 v111, v111, v111
	v_and_b32_e32 v112, 0xffff0000, v103
	v_fmac_f32_e32 v111, v110, v110
	v_lshlrev_b32_e32 v110, 16, v103
	v_mul_f32_e32 v112, v112, v112
	v_fmac_f32_e32 v112, v110, v110
	v_add_f32_e32 v110, v111, v112
	v_and_b32_e32 v112, 0xffff0000, v104
	v_lshlrev_b32_e32 v111, 16, v104
	v_mul_f32_e32 v112, v112, v112
	v_fmac_f32_e32 v112, v111, v111
	v_add_f32_e32 v110, v110, v112
	v_and_b32_e32 v112, 0xffff0000, v105
	v_lshlrev_b32_e32 v111, 16, v105
	v_mul_f32_e32 v112, v112, v112
	v_fmac_f32_e32 v112, v111, v111
	v_add_f32_e32 v112, v110, v112
	v_lshl_add_u64 v[110:111], s[36:37], 0, v[124:125]
	v_lshl_add_u64 v[110:111], v[110:111], 0, v[138:139]
	global_store_dwordx4 v[110:111], v[102:105], off
	v_pk_mul_f32 v[86:87], v[94:95], v[86:87]
	v_pk_mul_f32 v[88:89], v[88:89], v[122:123] op_sel_hi:[1,0]
	v_lshlrev_b32_e32 v102, 16, v154
	v_add_f32_e32 v86, v86, v102
	v_and_b32_e32 v102, 0xffff0000, v154
	v_pk_mul_f32 v[88:89], v[96:97], v[88:89]
	v_add_f32_e32 v87, v87, v102
	v_lshlrev_b32_e32 v102, 16, v155
	v_pk_mul_f32 v[82:83], v[82:83], v[122:123] op_sel_hi:[1,0]
	v_add_f32_e32 v88, v88, v102
	v_and_b32_e32 v102, 0xffff0000, v155
	v_pk_mul_f32 v[82:83], v[90:91], v[82:83]
	v_add_f32_e32 v89, v89, v102
	v_lshlrev_b32_e32 v102, 16, v156
	v_pk_mul_f32 v[84:85], v[84:85], v[122:123] op_sel_hi:[1,0]
	v_add_f32_e32 v82, v82, v102
	v_and_b32_e32 v102, 0xffff0000, v156
	v_pk_mul_f32 v[84:85], v[92:93], v[84:85]
	v_add_f32_e32 v83, v83, v102
	v_lshlrev_b32_e32 v102, 16, v157
	v_add_f32_e32 v102, v84, v102
	v_and_b32_e32 v84, 0xffff0000, v157
	v_add_f32_e32 v103, v85, v84
	v_cvt_pk_bf16_f32 v84, v86, v87
	v_cvt_pk_bf16_f32 v85, v88, v89
	v_cvt_pk_bf16_f32 v86, v82, v83
	v_cvt_pk_bf16_f32 v87, v102, v103
	global_store_dwordx4 v[110:111], v[84:87], off offset:256
	v_and_b32_e32 v83, 0xffff0000, v84
	v_lshlrev_b32_e32 v82, 16, v84
	v_mul_f32_e32 v83, v83, v83
	v_fmac_f32_e32 v83, v82, v82
	v_and_b32_e32 v88, 0xffff0000, v85
	v_add_f32_e32 v82, v112, v83
	v_lshlrev_b32_e32 v83, 16, v85
	v_mul_f32_e32 v88, v88, v88
	v_fmac_f32_e32 v88, v83, v83
	v_add_f32_e32 v82, v82, v88
	v_and_b32_e32 v88, 0xffff0000, v86
	v_lshlrev_b32_e32 v83, 16, v86
	v_mul_f32_e32 v88, v88, v88
	v_fmac_f32_e32 v88, v83, v83
	v_add_f32_e32 v82, v82, v88
	v_and_b32_e32 v88, 0xffff0000, v87
	v_lshlrev_b32_e32 v83, 16, v87
	v_mul_f32_e32 v88, v88, v88
	v_fmac_f32_e32 v88, v83, v83
	v_add_f32_e32 v82, v82, v88
	v_mov_b32_e32 v83, v82
	s_nop 1
	v_permlane16_swap_b32_e32 v83, v82
	s_waitcnt lgkmcnt(0)
	v_add_f32_e32 v82, v82, v83
	v_mov_b32_e32 v83, v82
	s_nop 1
	v_permlane32_swap_b32_e32 v83, v82
	s_and_saveexec_b64 s[10:11], s[0:1]
	s_cbranch_execz .LBB0_698
	s_waitcnt lgkmcnt(0)
	v_add_f32_e32 v82, v82, v83
	ds_write_b32 v234, v82
;     __device__ __forceinline__ void operator()(const f32x4 (&acc)[2][2][4][2], const pg8::Unit& u, int wr, int wc, int fr, int fq, LAS unsigned char* lds, int wid, int lane, const pg8::Unit& nxt, bool has_next, int ui) const {
;     ...
; #pragma unroll
;         for (int m = 0; m < 4; ++m) { RESNORM_ROWGROUP(0, m);
; #pragma unroll
;             for (int bj = 0; bj < 2; ++bj) xv[m][bj] = *(const v4u*)(X + (rowbase + rl0 + 128 + m * 16) * DM + col0 + bj * 128); }
.LBB0_698:
	s_or_b64 exec, exec, s[10:11]
	s_mov_b64 s[10:11], 0x10000
	v_add_co_u32_e32 v84, vcc, 0x10000, v140
	s_waitcnt lgkmcnt(0)
	v_lshl_add_u64 v[82:83], v[140:141], 0, s[10:11]
	v_addc_co_u32_e32 v85, vcc, 0, v141, vcc
	v_lshl_add_u32 v86, v194, 2, s56
	ds_read_b32 v102, v86
	global_load_dwordx4 v[86:89], v[84:85], off
	s_nop 0
	global_load_dwordx4 v[82:85], v[82:83], off offset:256
	v_lshl_add_u64 v[104:105], s[24:25], 0, v[194:195]
	v_lshlrev_b64 v[104:105], 11, v[104:105]
	s_waitcnt lgkmcnt(0)
	v_pk_mul_f32 v[78:79], v[78:79], v[102:103] op_sel_hi:[1,0]
	v_pk_mul_f32 v[80:81], v[80:81], v[102:103] op_sel_hi:[1,0]
	v_pk_mul_f32 v[78:79], v[106:107], v[78:79]
	v_pk_mul_f32 v[76:77], v[76:77], v[102:103] op_sel_hi:[1,0]
	v_pk_mul_f32 v[74:75], v[74:75], v[102:103] op_sel_hi:[1,0]
	v_lshlrev_b32_e32 v103, 16, v150
	v_add_f32_e32 v78, v78, v103
	v_and_b32_e32 v103, 0xffff0000, v150
	v_pk_mul_f32 v[80:81], v[108:109], v[80:81]
	v_add_f32_e32 v79, v79, v103
	v_lshlrev_b32_e32 v103, 16, v151
	v_add_f32_e32 v80, v80, v103
	v_and_b32_e32 v103, 0xffff0000, v151
	v_pk_mul_f32 v[74:75], v[98:99], v[74:75]
	v_add_f32_e32 v81, v81, v103
	v_lshlrev_b32_e32 v103, 16, v152
	v_add_f32_e32 v103, v74, v103
	v_and_b32_e32 v74, 0xffff0000, v152
	v_pk_mul_f32 v[76:77], v[100:101], v[76:77]
	v_add_f32_e32 v110, v75, v74
	v_lshlrev_b32_e32 v74, 16, v153
	v_add_f32_e32 v111, v76, v74
	v_and_b32_e32 v74, 0xffff0000, v153
	v_add_f32_e32 v77, v77, v74
	v_cvt_pk_bf16_f32 v74, v78, v79
	v_cvt_pk_bf16_f32 v75, v80, v81
	v_cvt_pk_bf16_f32 v76, v103, v110
	v_cvt_pk_bf16_f32 v77, v111, v77
	v_pk_mul_f32 v[70:71], v[70:71], v[102:103] op_sel_hi:[1,0]
	v_and_b32_e32 v79, 0xffff0000, v74
	v_lshlrev_b32_e32 v78, 16, v74
	v_mul_f32_e32 v79, v79, v79
	v_and_b32_e32 v80, 0xffff0000, v75
	v_fmac_f32_e32 v79, v78, v78
	v_lshlrev_b32_e32 v78, 16, v75
	v_mul_f32_e32 v80, v80, v80
	v_fmac_f32_e32 v80, v78, v78
	v_add_f32_e32 v78, v79, v80
	v_and_b32_e32 v80, 0xffff0000, v76
	v_lshlrev_b32_e32 v79, 16, v76
	v_mul_f32_e32 v80, v80, v80
	v_fmac_f32_e32 v80, v79, v79
	v_add_f32_e32 v78, v78, v80
	v_and_b32_e32 v80, 0xffff0000, v77
	v_lshlrev_b32_e32 v79, 16, v77
	v_mul_f32_e32 v80, v80, v80
	v_fmac_f32_e32 v80, v79, v79
	v_add_f32_e32 v80, v78, v80
	v_lshl_add_u64 v[78:79], s[36:37], 0, v[104:105]
	v_lshl_add_u64 v[78:79], v[78:79], 0, v[138:139]
	global_store_dwordx4 v[78:79], v[74:77], off
	v_pk_mul_f32 v[70:71], v[94:95], v[70:71]
	v_pk_mul_f32 v[72:73], v[72:73], v[102:103] op_sel_hi:[1,0]
	v_lshlrev_b32_e32 v74, 16, v146
	v_add_f32_e32 v70, v70, v74
	v_and_b32_e32 v74, 0xffff0000, v146
	v_pk_mul_f32 v[72:73], v[96:97], v[72:73]
	v_add_f32_e32 v71, v71, v74
	v_lshlrev_b32_e32 v74, 16, v147
	v_pk_mul_f32 v[66:67], v[66:67], v[102:103] op_sel_hi:[1,0]
	v_add_f32_e32 v72, v72, v74
	v_and_b32_e32 v74, 0xffff0000, v147
	v_pk_mul_f32 v[66:67], v[90:91], v[66:67]
	v_add_f32_e32 v73, v73, v74
	v_lshlrev_b32_e32 v74, 16, v148
	v_pk_mul_f32 v[68:69], v[68:69], v[102:103] op_sel_hi:[1,0]
	v_add_f32_e32 v66, v66, v74
	v_and_b32_e32 v74, 0xffff0000, v148
	v_pk_mul_f32 v[68:69], v[92:93], v[68:69]
	v_add_f32_e32 v67, v67, v74
	v_lshlrev_b32_e32 v74, 16, v149
	v_add_f32_e32 v74, v68, v74
	v_and_b32_e32 v68, 0xffff0000, v149
	v_add_f32_e32 v75, v69, v68
	v_cvt_pk_bf16_f32 v68, v70, v71
	v_cvt_pk_bf16_f32 v69, v72, v73
	v_cvt_pk_bf16_f32 v70, v66, v67
	v_cvt_pk_bf16_f32 v71, v74, v75
	global_store_dwordx4 v[78:79], v[68:71], off offset:256
	v_and_b32_e32 v67, 0xffff0000, v68
	v_lshlrev_b32_e32 v66, 16, v68
	v_mul_f32_e32 v67, v67, v67
	v_fmac_f32_e32 v67, v66, v66
	v_and_b32_e32 v72, 0xffff0000, v69
	v_add_f32_e32 v66, v80, v67
	v_lshlrev_b32_e32 v67, 16, v69
	v_mul_f32_e32 v72, v72, v72
	v_fmac_f32_e32 v72, v67, v67
	v_add_f32_e32 v66, v66, v72
	v_and_b32_e32 v72, 0xffff0000, v70
	v_lshlrev_b32_e32 v67, 16, v70
	v_mul_f32_e32 v72, v72, v72
	v_fmac_f32_e32 v72, v67, v67
	v_add_f32_e32 v66, v66, v72
	v_and_b32_e32 v72, 0xffff0000, v71
	v_lshlrev_b32_e32 v67, 16, v71
	v_mul_f32_e32 v72, v72, v72
	v_fmac_f32_e32 v72, v67, v67
	v_add_f32_e32 v66, v66, v72
	v_mov_b32_e32 v67, v66
	s_nop 1
	v_permlane16_swap_b32_e32 v67, v66
	s_waitcnt lgkmcnt(0)
	v_add_f32_e32 v66, v66, v67
	v_mov_b32_e32 v67, v66
	s_nop 1
	v_permlane32_swap_b32_e32 v67, v66
	s_and_saveexec_b64 s[10:11], s[0:1]
	s_cbranch_execz .LBB0_700
	s_waitcnt lgkmcnt(0)
	v_add_f32_e32 v66, v66, v67
	ds_write_b32 v235, v66
;     __device__ __forceinline__ void operator()(const f32x4 (&acc)[2][2][4][2], const pg8::Unit& u, int wr, int wc, int fr, int fq, LAS unsigned char* lds, int wid, int lane, const pg8::Unit& nxt, bool has_next, int ui) const {
;     ...
; #pragma unroll
;         for (int m = 0; m < 4; ++m) { RESNORM_ROWGROUP(0, m);
; #pragma unroll
;             for (int bj = 0; bj < 2; ++bj) xv[m][bj] = *(const v4u*)(X + (rowbase + rl0 + 128 + m * 16) * DM + col0 + bj * 128); }
; #pragma unroll
;         for (int m = 0; m < 4; ++m) RESNORM_ROWGROUP(1, m);
.LBB0_700:
	s_or_b64 exec, exec, s[10:11]
	s_mov_b64 s[10:11], 0x18000
	v_add_co_u32_e32 v68, vcc, 0x18000, v140
	s_waitcnt lgkmcnt(0)
	v_lshl_add_u64 v[66:67], v[140:141], 0, s[10:11]
	v_addc_co_u32_e32 v69, vcc, 0, v141, vcc
	v_lshl_add_u32 v70, v196, 2, s56
	ds_read_b32 v74, v70
	global_load_dwordx4 v[70:73], v[68:69], off
	s_nop 0
	global_load_dwordx4 v[66:69], v[66:67], off offset:256
	v_lshl_add_u64 v[76:77], s[24:25], 0, v[196:197]
	v_lshlrev_b64 v[76:77], 11, v[76:77]
	s_waitcnt lgkmcnt(0)
	v_pk_mul_f32 v[62:63], v[62:63], v[74:75] op_sel_hi:[1,0]
	v_pk_mul_f32 v[64:65], v[64:65], v[74:75] op_sel_hi:[1,0]
	v_pk_mul_f32 v[62:63], v[106:107], v[62:63]
	v_pk_mul_f32 v[60:61], v[60:61], v[74:75] op_sel_hi:[1,0]
	v_pk_mul_f32 v[58:59], v[58:59], v[74:75] op_sel_hi:[1,0]
	s_waitcnt vmcnt(13)
	v_lshlrev_b32_e32 v75, 16, v134
	v_add_f32_e32 v62, v62, v75
	v_and_b32_e32 v75, 0xffff0000, v134
	v_pk_mul_f32 v[64:65], v[108:109], v[64:65]
	v_add_f32_e32 v63, v63, v75
	v_lshlrev_b32_e32 v75, 16, v135
	v_add_f32_e32 v64, v64, v75
	v_and_b32_e32 v75, 0xffff0000, v135
	v_pk_mul_f32 v[58:59], v[98:99], v[58:59]
	v_add_f32_e32 v65, v65, v75
	v_lshlrev_b32_e32 v75, 16, v136
	v_add_f32_e32 v75, v58, v75
	v_and_b32_e32 v58, 0xffff0000, v136
	v_pk_mul_f32 v[60:61], v[100:101], v[60:61]
	v_add_f32_e32 v78, v59, v58
	v_lshlrev_b32_e32 v58, 16, v137
	v_add_f32_e32 v79, v60, v58
	v_and_b32_e32 v58, 0xffff0000, v137
	v_add_f32_e32 v61, v61, v58
	v_cvt_pk_bf16_f32 v58, v62, v63
	v_cvt_pk_bf16_f32 v59, v64, v65
	v_cvt_pk_bf16_f32 v60, v75, v78
	v_cvt_pk_bf16_f32 v61, v79, v61
	v_pk_mul_f32 v[54:55], v[54:55], v[74:75] op_sel_hi:[1,0]
	v_and_b32_e32 v63, 0xffff0000, v58
	v_lshlrev_b32_e32 v62, 16, v58
	v_mul_f32_e32 v63, v63, v63
	v_and_b32_e32 v64, 0xffff0000, v59
	v_fmac_f32_e32 v63, v62, v62
	v_lshlrev_b32_e32 v62, 16, v59
	v_mul_f32_e32 v64, v64, v64
	v_fmac_f32_e32 v64, v62, v62
	v_add_f32_e32 v62, v63, v64
	v_and_b32_e32 v64, 0xffff0000, v60
	v_lshlrev_b32_e32 v63, 16, v60
	v_mul_f32_e32 v64, v64, v64
	v_fmac_f32_e32 v64, v63, v63
	v_add_f32_e32 v62, v62, v64
	v_and_b32_e32 v64, 0xffff0000, v61
	v_lshlrev_b32_e32 v63, 16, v61
	v_mul_f32_e32 v64, v64, v64
	v_fmac_f32_e32 v64, v63, v63
	v_add_f32_e32 v64, v62, v64
	v_lshl_add_u64 v[62:63], s[36:37], 0, v[76:77]
	v_lshl_add_u64 v[62:63], v[62:63], 0, v[138:139]
	global_store_dwordx4 v[62:63], v[58:61], off
	v_pk_mul_f32 v[54:55], v[94:95], v[54:55]
	v_pk_mul_f32 v[56:57], v[56:57], v[74:75] op_sel_hi:[1,0]
	s_waitcnt vmcnt(13)
	v_lshlrev_b32_e32 v58, 16, v130
	v_add_f32_e32 v54, v54, v58
	v_and_b32_e32 v58, 0xffff0000, v130
	v_pk_mul_f32 v[56:57], v[96:97], v[56:57]
	v_add_f32_e32 v55, v55, v58
	v_lshlrev_b32_e32 v58, 16, v131
	v_pk_mul_f32 v[50:51], v[50:51], v[74:75] op_sel_hi:[1,0]
	v_add_f32_e32 v56, v56, v58
	v_and_b32_e32 v58, 0xffff0000, v131
	v_pk_mul_f32 v[50:51], v[90:91], v[50:51]
	v_add_f32_e32 v57, v57, v58
	v_lshlrev_b32_e32 v58, 16, v132
	v_pk_mul_f32 v[52:53], v[52:53], v[74:75] op_sel_hi:[1,0]
	v_add_f32_e32 v50, v50, v58
	v_and_b32_e32 v58, 0xffff0000, v132
	v_pk_mul_f32 v[52:53], v[92:93], v[52:53]
	v_add_f32_e32 v51, v51, v58
	v_lshlrev_b32_e32 v58, 16, v133
	v_add_f32_e32 v58, v52, v58
	v_and_b32_e32 v52, 0xffff0000, v133
	v_add_f32_e32 v59, v53, v52
	v_cvt_pk_bf16_f32 v52, v54, v55
	v_cvt_pk_bf16_f32 v53, v56, v57
	v_cvt_pk_bf16_f32 v54, v50, v51
	v_cvt_pk_bf16_f32 v55, v58, v59
	global_store_dwordx4 v[62:63], v[52:55], off offset:256
	v_and_b32_e32 v51, 0xffff0000, v52
	v_lshlrev_b32_e32 v50, 16, v52
	v_mul_f32_e32 v51, v51, v51
	v_fmac_f32_e32 v51, v50, v50
	v_and_b32_e32 v56, 0xffff0000, v53
	v_add_f32_e32 v50, v64, v51
	v_lshlrev_b32_e32 v51, 16, v53
	v_mul_f32_e32 v56, v56, v56
	v_fmac_f32_e32 v56, v51, v51
	v_add_f32_e32 v50, v50, v56
	v_and_b32_e32 v56, 0xffff0000, v54
	v_lshlrev_b32_e32 v51, 16, v54
	v_mul_f32_e32 v56, v56, v56
	v_fmac_f32_e32 v56, v51, v51
	v_add_f32_e32 v50, v50, v56
	v_and_b32_e32 v56, 0xffff0000, v55
	v_lshlrev_b32_e32 v51, 16, v55
	v_mul_f32_e32 v56, v56, v56
	v_fmac_f32_e32 v56, v51, v51
	v_add_f32_e32 v50, v50, v56
	v_mov_b32_e32 v51, v50
	s_nop 1
	v_permlane16_swap_b32_e32 v51, v50
	s_waitcnt lgkmcnt(0)
	v_add_f32_e32 v50, v50, v51
	v_mov_b32_e32 v51, v50
	s_nop 1
	v_permlane32_swap_b32_e32 v51, v50
	s_and_saveexec_b64 s[10:11], s[0:1]
	s_cbranch_execz .LBB0_702
	s_waitcnt lgkmcnt(0)
	v_add_f32_e32 v50, v50, v51
	ds_write_b32 v236, v50
;     __device__ __forceinline__ void operator()(const f32x4 (&acc)[2][2][4][2], const pg8::Unit& u, int wr, int wc, int fr, int fq, LAS unsigned char* lds, int wid, int lane, const pg8::Unit& nxt, bool has_next, int ui) const {
;     ...
; #pragma unroll
;         for (int m = 0; m < 4; ++m) { RESNORM_ROWGROUP(0, m);
; #pragma unroll
;             for (int bj = 0; bj < 2; ++bj) xv[m][bj] = *(const v4u*)(X + (rowbase + rl0 + 128 + m * 16) * DM + col0 + bj * 128); }
; #pragma unroll
;         for (int m = 0; m < 4; ++m) RESNORM_ROWGROUP(1, m);
.LBB0_702:
	s_or_b64 exec, exec, s[10:11]
	v_lshl_add_u32 v50, v198, 2, s56
	ds_read_b32 v50, v50
	v_lshl_add_u64 v[52:53], s[24:25], 0, v[198:199]
	v_lshlrev_b64 v[52:53], 11, v[52:53]
	s_waitcnt lgkmcnt(0)
	v_pk_mul_f32 v[46:47], v[46:47], v[50:51] op_sel_hi:[1,0]
	v_pk_mul_f32 v[48:49], v[48:49], v[50:51] op_sel_hi:[1,0]
	v_pk_mul_f32 v[46:47], v[106:107], v[46:47]
	v_pk_mul_f32 v[44:45], v[44:45], v[50:51] op_sel_hi:[1,0]
	v_pk_mul_f32 v[42:43], v[42:43], v[50:51] op_sel_hi:[1,0]
	s_waitcnt vmcnt(11)
	v_lshlrev_b32_e32 v51, 16, v118
	v_add_f32_e32 v46, v46, v51
	v_and_b32_e32 v51, 0xffff0000, v118
	v_pk_mul_f32 v[48:49], v[108:109], v[48:49]
	v_add_f32_e32 v47, v47, v51
	v_lshlrev_b32_e32 v51, 16, v119
	v_add_f32_e32 v48, v48, v51
	v_and_b32_e32 v51, 0xffff0000, v119
	v_pk_mul_f32 v[42:43], v[98:99], v[42:43]
	v_add_f32_e32 v49, v49, v51
	v_lshlrev_b32_e32 v51, 16, v120
	v_add_f32_e32 v51, v42, v51
	v_and_b32_e32 v42, 0xffff0000, v120
	v_pk_mul_f32 v[44:45], v[100:101], v[44:45]
	v_add_f32_e32 v54, v43, v42
	v_lshlrev_b32_e32 v42, 16, v121
	v_add_f32_e32 v55, v44, v42
	v_and_b32_e32 v42, 0xffff0000, v121
	v_add_f32_e32 v45, v45, v42
	v_cvt_pk_bf16_f32 v42, v46, v47
	v_cvt_pk_bf16_f32 v43, v48, v49
	v_cvt_pk_bf16_f32 v44, v51, v54
	v_cvt_pk_bf16_f32 v45, v55, v45
	v_pk_mul_f32 v[38:39], v[38:39], v[50:51] op_sel_hi:[1,0]
	v_and_b32_e32 v47, 0xffff0000, v42
	v_lshlrev_b32_e32 v46, 16, v42
	v_mul_f32_e32 v47, v47, v47
	v_and_b32_e32 v48, 0xffff0000, v43
	v_fmac_f32_e32 v47, v46, v46
	v_lshlrev_b32_e32 v46, 16, v43
	v_mul_f32_e32 v48, v48, v48
	v_fmac_f32_e32 v48, v46, v46
	v_add_f32_e32 v46, v47, v48
	v_and_b32_e32 v48, 0xffff0000, v44
	v_lshlrev_b32_e32 v47, 16, v44
	v_mul_f32_e32 v48, v48, v48
	v_fmac_f32_e32 v48, v47, v47
	v_add_f32_e32 v46, v46, v48
	v_and_b32_e32 v48, 0xffff0000, v45
	v_lshlrev_b32_e32 v47, 16, v45
	v_mul_f32_e32 v48, v48, v48
	v_fmac_f32_e32 v48, v47, v47
	v_add_f32_e32 v48, v46, v48
	v_lshl_add_u64 v[46:47], s[36:37], 0, v[52:53]
	v_lshl_add_u64 v[46:47], v[208:209], 1, v[46:47]
	global_store_dwordx4 v[46:47], v[42:45], off
	v_pk_mul_f32 v[38:39], v[94:95], v[38:39]
	v_pk_mul_f32 v[40:41], v[40:41], v[50:51] op_sel_hi:[1,0]
	s_waitcnt vmcnt(11)
	v_lshlrev_b32_e32 v42, 16, v114
	v_add_f32_e32 v38, v38, v42
	v_and_b32_e32 v42, 0xffff0000, v114
	v_pk_mul_f32 v[40:41], v[96:97], v[40:41]
	v_add_f32_e32 v39, v39, v42
	v_lshlrev_b32_e32 v42, 16, v115
	v_pk_mul_f32 v[34:35], v[34:35], v[50:51] op_sel_hi:[1,0]
	v_add_f32_e32 v40, v40, v42
	v_and_b32_e32 v42, 0xffff0000, v115
	v_pk_mul_f32 v[34:35], v[90:91], v[34:35]
	v_add_f32_e32 v41, v41, v42
	v_lshlrev_b32_e32 v42, 16, v116
	v_pk_mul_f32 v[36:37], v[36:37], v[50:51] op_sel_hi:[1,0]
	v_add_f32_e32 v34, v34, v42
	v_and_b32_e32 v42, 0xffff0000, v116
	v_pk_mul_f32 v[36:37], v[92:93], v[36:37]
	v_add_f32_e32 v35, v35, v42
	v_lshlrev_b32_e32 v42, 16, v117
	v_add_f32_e32 v42, v36, v42
	v_and_b32_e32 v36, 0xffff0000, v117
	v_add_f32_e32 v43, v37, v36
	v_cvt_pk_bf16_f32 v36, v38, v39
	v_cvt_pk_bf16_f32 v37, v40, v41
	v_cvt_pk_bf16_f32 v38, v34, v35
	v_cvt_pk_bf16_f32 v39, v42, v43
	global_store_dwordx4 v[46:47], v[36:39], off offset:256
	v_and_b32_e32 v35, 0xffff0000, v36
	v_lshlrev_b32_e32 v34, 16, v36
	v_mul_f32_e32 v35, v35, v35
	v_fmac_f32_e32 v35, v34, v34
	v_and_b32_e32 v40, 0xffff0000, v37
	v_add_f32_e32 v34, v48, v35
	v_lshlrev_b32_e32 v35, 16, v37
	v_mul_f32_e32 v40, v40, v40
	v_fmac_f32_e32 v40, v35, v35
	v_add_f32_e32 v34, v34, v40
	v_and_b32_e32 v40, 0xffff0000, v38
	v_lshlrev_b32_e32 v35, 16, v38
	v_mul_f32_e32 v40, v40, v40
	v_fmac_f32_e32 v40, v35, v35
	v_add_f32_e32 v34, v34, v40
	v_and_b32_e32 v40, 0xffff0000, v39
	v_lshlrev_b32_e32 v35, 16, v39
	v_mul_f32_e32 v40, v40, v40
	v_fmac_f32_e32 v40, v35, v35
	v_add_f32_e32 v34, v34, v40
	v_mov_b32_e32 v35, v34
	s_nop 1
	v_permlane16_swap_b32_e32 v35, v34
	s_waitcnt lgkmcnt(0)
	v_add_f32_e32 v34, v34, v35
	v_mov_b32_e32 v35, v34
	s_nop 1
	v_permlane32_swap_b32_e32 v35, v34
	s_and_saveexec_b64 s[10:11], s[0:1]
	s_cbranch_execz .LBB0_704
	s_waitcnt lgkmcnt(0)
	v_add_f32_e32 v34, v34, v35
	ds_write_b32 v237, v34
.LBB0_704:
	s_or_b64 exec, exec, s[10:11]
	v_lshl_add_u32 v34, v200, 2, s56
	ds_read_b32 v34, v34
	v_lshl_add_u64 v[36:37], s[24:25], 0, v[200:201]
	v_lshlrev_b64 v[36:37], 11, v[36:37]
	s_waitcnt lgkmcnt(0)
	v_pk_mul_f32 v[30:31], v[30:31], v[34:35] op_sel_hi:[1,0]
	v_pk_mul_f32 v[32:33], v[32:33], v[34:35] op_sel_hi:[1,0]
	v_pk_mul_f32 v[30:31], v[106:107], v[30:31]
	v_pk_mul_f32 v[28:29], v[28:29], v[34:35] op_sel_hi:[1,0]
	v_pk_mul_f32 v[26:27], v[26:27], v[34:35] op_sel_hi:[1,0]
	s_waitcnt vmcnt(9)
	v_lshlrev_b32_e32 v35, 16, v86
	v_add_f32_e32 v30, v30, v35
	v_and_b32_e32 v35, 0xffff0000, v86
	v_pk_mul_f32 v[32:33], v[108:109], v[32:33]
	v_add_f32_e32 v31, v31, v35
	v_lshlrev_b32_e32 v35, 16, v87
	v_add_f32_e32 v32, v32, v35
	v_and_b32_e32 v35, 0xffff0000, v87
	v_pk_mul_f32 v[26:27], v[98:99], v[26:27]
	v_add_f32_e32 v33, v33, v35
	v_lshlrev_b32_e32 v35, 16, v88
	v_add_f32_e32 v35, v26, v35
	v_and_b32_e32 v26, 0xffff0000, v88
	v_pk_mul_f32 v[28:29], v[100:101], v[28:29]
	v_add_f32_e32 v38, v27, v26
	v_lshlrev_b32_e32 v26, 16, v89
	v_add_f32_e32 v39, v28, v26
	v_and_b32_e32 v26, 0xffff0000, v89
	v_add_f32_e32 v29, v29, v26
	v_cvt_pk_bf16_f32 v26, v30, v31
	v_cvt_pk_bf16_f32 v27, v32, v33
	v_cvt_pk_bf16_f32 v28, v35, v38
	v_cvt_pk_bf16_f32 v29, v39, v29
	v_pk_mul_f32 v[22:23], v[22:23], v[34:35] op_sel_hi:[1,0]
	v_and_b32_e32 v31, 0xffff0000, v26
	v_lshlrev_b32_e32 v30, 16, v26
	v_mul_f32_e32 v31, v31, v31
	v_and_b32_e32 v32, 0xffff0000, v27
	v_fmac_f32_e32 v31, v30, v30
	v_lshlrev_b32_e32 v30, 16, v27
	v_mul_f32_e32 v32, v32, v32
	v_fmac_f32_e32 v32, v30, v30
	v_add_f32_e32 v30, v31, v32
	v_and_b32_e32 v32, 0xffff0000, v28
	v_lshlrev_b32_e32 v31, 16, v28
	v_mul_f32_e32 v32, v32, v32
	v_fmac_f32_e32 v32, v31, v31
	v_add_f32_e32 v30, v30, v32
	v_and_b32_e32 v32, 0xffff0000, v29
	v_lshlrev_b32_e32 v31, 16, v29
	v_mul_f32_e32 v32, v32, v32
	v_fmac_f32_e32 v32, v31, v31
	v_add_f32_e32 v32, v30, v32
	v_lshl_add_u64 v[30:31], s[36:37], 0, v[36:37]
	v_lshl_add_u64 v[30:31], v[208:209], 1, v[30:31]
	global_store_dwordx4 v[30:31], v[26:29], off
	v_pk_mul_f32 v[22:23], v[94:95], v[22:23]
	v_pk_mul_f32 v[24:25], v[24:25], v[34:35] op_sel_hi:[1,0]
	s_waitcnt vmcnt(9)
;     __device__ __forceinline__ void operator()(const f32x4 (&acc)[2][2][4][2], const pg8::Unit& u, int wr, int wc, int fr, int fq, LAS unsigned char* lds, int wid, int lane, const pg8::Unit& nxt, bool has_next, int ui) const {
;     ...
; #pragma unroll
;         for (int m = 0; m < 4; ++m) { RESNORM_ROWGROUP(0, m);
; #pragma unroll
;             for (int bj = 0; bj < 2; ++bj) xv[m][bj] = *(const v4u*)(X + (rowbase + rl0 + 128 + m * 16) * DM + col0 + bj * 128); }
; #pragma unroll
;         for (int m = 0; m < 4; ++m) RESNORM_ROWGROUP(1, m);
	v_lshlrev_b32_e32 v26, 16, v82
	v_add_f32_e32 v22, v22, v26
	v_and_b32_e32 v26, 0xffff0000, v82
	v_pk_mul_f32 v[24:25], v[96:97], v[24:25]
	v_add_f32_e32 v23, v23, v26
	v_lshlrev_b32_e32 v26, 16, v83
	v_pk_mul_f32 v[18:19], v[18:19], v[34:35] op_sel_hi:[1,0]
	v_add_f32_e32 v24, v24, v26
	v_and_b32_e32 v26, 0xffff0000, v83
	v_pk_mul_f32 v[18:19], v[90:91], v[18:19]
	v_add_f32_e32 v25, v25, v26
	v_lshlrev_b32_e32 v26, 16, v84
	v_pk_mul_f32 v[20:21], v[20:21], v[34:35] op_sel_hi:[1,0]
	v_add_f32_e32 v18, v18, v26
	v_and_b32_e32 v26, 0xffff0000, v84
	v_pk_mul_f32 v[20:21], v[92:93], v[20:21]
	v_add_f32_e32 v19, v19, v26
	v_lshlrev_b32_e32 v26, 16, v85
	v_add_f32_e32 v26, v20, v26
	v_and_b32_e32 v20, 0xffff0000, v85
	v_add_f32_e32 v27, v21, v20
	v_cvt_pk_bf16_f32 v20, v22, v23
	v_cvt_pk_bf16_f32 v21, v24, v25
	v_cvt_pk_bf16_f32 v22, v18, v19
	v_cvt_pk_bf16_f32 v23, v26, v27
	global_store_dwordx4 v[30:31], v[20:23], off offset:256
	v_and_b32_e32 v19, 0xffff0000, v20
	v_lshlrev_b32_e32 v18, 16, v20
	v_mul_f32_e32 v19, v19, v19
	v_fmac_f32_e32 v19, v18, v18
	v_and_b32_e32 v24, 0xffff0000, v21
	v_add_f32_e32 v18, v32, v19
	v_lshlrev_b32_e32 v19, 16, v21
	v_mul_f32_e32 v24, v24, v24
	v_fmac_f32_e32 v24, v19, v19
	v_add_f32_e32 v18, v18, v24
	v_and_b32_e32 v24, 0xffff0000, v22
	v_lshlrev_b32_e32 v19, 16, v22
	v_mul_f32_e32 v24, v24, v24
	v_fmac_f32_e32 v24, v19, v19
	v_add_f32_e32 v18, v18, v24
	v_and_b32_e32 v24, 0xffff0000, v23
	v_lshlrev_b32_e32 v19, 16, v23
	v_mul_f32_e32 v24, v24, v24
	v_fmac_f32_e32 v24, v19, v19
	v_add_f32_e32 v18, v18, v24
	v_mov_b32_e32 v19, v18
	s_nop 1
	v_permlane16_swap_b32_e32 v19, v18
	s_waitcnt lgkmcnt(0)
	v_add_f32_e32 v18, v18, v19
	v_mov_b32_e32 v19, v18
	s_nop 1
	v_permlane32_swap_b32_e32 v19, v18
	s_and_saveexec_b64 s[10:11], s[0:1]
	s_cbranch_execz .LBB0_706
	s_waitcnt lgkmcnt(0)
	v_add_f32_e32 v18, v18, v19
	ds_write_b32 v238, v18
.LBB0_706:
	s_or_b64 exec, exec, s[10:11]
	v_lshl_add_u32 v18, v202, 2, s56
	ds_read_b32 v18, v18
	v_lshl_add_u64 v[20:21], s[24:25], 0, v[202:203]
	v_lshlrev_b64 v[20:21], 11, v[20:21]
	s_waitcnt lgkmcnt(0)
	v_pk_mul_f32 v[14:15], v[14:15], v[18:19] op_sel_hi:[1,0]
	v_pk_mul_f32 v[16:17], v[16:17], v[18:19] op_sel_hi:[1,0]
	v_pk_mul_f32 v[14:15], v[106:107], v[14:15]
	v_pk_mul_f32 v[12:13], v[12:13], v[18:19] op_sel_hi:[1,0]
	v_pk_mul_f32 v[10:11], v[10:11], v[18:19] op_sel_hi:[1,0]
	s_waitcnt vmcnt(7)
	v_lshlrev_b32_e32 v19, 16, v70
	v_add_f32_e32 v14, v14, v19
	v_and_b32_e32 v19, 0xffff0000, v70
	v_pk_mul_f32 v[16:17], v[108:109], v[16:17]
	v_add_f32_e32 v15, v15, v19
	v_lshlrev_b32_e32 v19, 16, v71
	v_add_f32_e32 v16, v16, v19
	v_and_b32_e32 v19, 0xffff0000, v71
	v_pk_mul_f32 v[10:11], v[98:99], v[10:11]
	v_add_f32_e32 v17, v17, v19
	v_lshlrev_b32_e32 v19, 16, v72
	v_add_f32_e32 v19, v10, v19
	v_and_b32_e32 v10, 0xffff0000, v72
	v_pk_mul_f32 v[12:13], v[100:101], v[12:13]
	v_add_f32_e32 v22, v11, v10
	v_lshlrev_b32_e32 v10, 16, v73
	v_add_f32_e32 v23, v12, v10
	v_and_b32_e32 v10, 0xffff0000, v73
	v_add_f32_e32 v13, v13, v10
	v_cvt_pk_bf16_f32 v10, v14, v15
	v_cvt_pk_bf16_f32 v11, v16, v17
	v_cvt_pk_bf16_f32 v12, v19, v22
	v_cvt_pk_bf16_f32 v13, v23, v13
	v_pk_mul_f32 v[6:7], v[6:7], v[18:19] op_sel_hi:[1,0]
	v_and_b32_e32 v15, 0xffff0000, v10
	v_lshlrev_b32_e32 v14, 16, v10
	v_mul_f32_e32 v15, v15, v15
	v_and_b32_e32 v16, 0xffff0000, v11
	v_fmac_f32_e32 v15, v14, v14
	v_lshlrev_b32_e32 v14, 16, v11
	v_mul_f32_e32 v16, v16, v16
	v_fmac_f32_e32 v16, v14, v14
	v_add_f32_e32 v14, v15, v16
	v_and_b32_e32 v16, 0xffff0000, v12
	v_lshlrev_b32_e32 v15, 16, v12
	v_mul_f32_e32 v16, v16, v16
	v_fmac_f32_e32 v16, v15, v15
	v_add_f32_e32 v14, v14, v16
	v_and_b32_e32 v16, 0xffff0000, v13
	v_lshlrev_b32_e32 v15, 16, v13
	v_mul_f32_e32 v16, v16, v16
	v_fmac_f32_e32 v16, v15, v15
	v_add_f32_e32 v16, v14, v16
	v_lshl_add_u64 v[14:15], s[36:37], 0, v[20:21]
	v_lshl_add_u64 v[14:15], v[208:209], 1, v[14:15]
	global_store_dwordx4 v[14:15], v[10:13], off
	v_pk_mul_f32 v[6:7], v[94:95], v[6:7]
	v_pk_mul_f32 v[8:9], v[8:9], v[18:19] op_sel_hi:[1,0]
	s_waitcnt vmcnt(7)
	v_lshlrev_b32_e32 v10, 16, v66
	v_add_f32_e32 v6, v6, v10
	v_and_b32_e32 v10, 0xffff0000, v66
	v_pk_mul_f32 v[8:9], v[96:97], v[8:9]
	v_add_f32_e32 v7, v7, v10
	v_lshlrev_b32_e32 v10, 16, v67
	v_pk_mul_f32 v[2:3], v[2:3], v[18:19] op_sel_hi:[1,0]
	v_add_f32_e32 v8, v8, v10
	v_and_b32_e32 v10, 0xffff0000, v67
	v_pk_mul_f32 v[2:3], v[90:91], v[2:3]
	v_add_f32_e32 v9, v9, v10
	v_lshlrev_b32_e32 v10, 16, v68
	v_pk_mul_f32 v[4:5], v[4:5], v[18:19] op_sel_hi:[1,0]
	v_add_f32_e32 v2, v2, v10
	v_and_b32_e32 v10, 0xffff0000, v68
	v_pk_mul_f32 v[4:5], v[92:93], v[4:5]
	v_add_f32_e32 v3, v3, v10
	v_lshlrev_b32_e32 v10, 16, v69
	v_add_f32_e32 v10, v4, v10
	v_and_b32_e32 v4, 0xffff0000, v69
	v_add_f32_e32 v11, v5, v4
	v_cvt_pk_bf16_f32 v4, v6, v7
	v_cvt_pk_bf16_f32 v5, v8, v9
	v_cvt_pk_bf16_f32 v6, v2, v3
	v_cvt_pk_bf16_f32 v7, v10, v11
	global_store_dwordx4 v[14:15], v[4:7], off offset:256
	v_and_b32_e32 v3, 0xffff0000, v4
	v_lshlrev_b32_e32 v2, 16, v4
	v_mul_f32_e32 v3, v3, v3
	v_fmac_f32_e32 v3, v2, v2
	v_and_b32_e32 v8, 0xffff0000, v5
	v_add_f32_e32 v2, v16, v3
	v_lshlrev_b32_e32 v3, 16, v5
	v_mul_f32_e32 v8, v8, v8
	v_fmac_f32_e32 v8, v3, v3
	v_add_f32_e32 v2, v2, v8
	v_and_b32_e32 v8, 0xffff0000, v6
	v_lshlrev_b32_e32 v3, 16, v6
	v_mul_f32_e32 v8, v8, v8
	v_fmac_f32_e32 v8, v3, v3
	v_add_f32_e32 v2, v2, v8
	v_and_b32_e32 v8, 0xffff0000, v7
	v_lshlrev_b32_e32 v3, 16, v7
	v_mul_f32_e32 v8, v8, v8
	v_fmac_f32_e32 v8, v3, v3
	v_add_f32_e32 v2, v2, v8
	v_mov_b32_e32 v3, v2
	s_nop 1
	v_permlane16_swap_b32_e32 v3, v2
	s_waitcnt lgkmcnt(0)
	v_add_f32_e32 v2, v2, v3
	v_mov_b32_e32 v3, v2
	s_nop 1
	v_permlane32_swap_b32_e32 v3, v2
	s_and_saveexec_b64 s[10:11], s[0:1]
	s_cbranch_execz .LBB0_708
	s_waitcnt lgkmcnt(0)
	v_add_f32_e32 v2, v2, v3
	ds_write_b32 v239, v2

;     __device__ __forceinline__ void operator()(const f32x4 (&acc)[2][2][4][2], const pg8::Unit& u, int wr, int wc, int fr, int fq, LAS unsigned char* lds, int wid, int lane, const pg8::Unit& nxt, bool has_next, int ui) const {
;     ...
;         v4u xv[4][2];
; #pragma unroll
;         for (int m = 0; m < 4; ++m)
; #pragma unroll
;             for (int bj = 0; bj < 2; ++bj) xv[m][bj] = *(const v4u*)(X + (rowbase + rl0 + m * 16) * DM + col0 + bj * 128);
;         f32x4 gv[2][2];
; #pragma unroll
;         for (int bj = 0; bj < 2; ++bj)
; #pragma unroll
;             for (int n = 0; n < 2; ++n) gv[bj][n] = *(const f32x4*)(gpost + col0 + bj * 128 + 4 * n);
; #pragma unroll
;         for (int ai = 0; ai < 2; ++ai)
; #pragma unroll
;             for (int m = 0; m < 4; ++m) { float ss = 0.f;
; #pragma unroll
;                 for (int bj = 0; bj < 2; ++bj)
; #pragma unroll
;                     for (int n = 0; n < 2; ++n) { const f32x4 v = acc[ai][bj][m][n]; ss += (v[0] * v[0] + v[1] * v[1]) + (v[2] * v[2] + v[3] * v[3]); }
;                 ss += __shfl_xor(ss, 16); ss += __shfl_xor(ss, 32);
;                 if (fq == 0) P[(rl0 + ai * 128 + m * 16) * 4 + wc] = ss; }
.LBB0_736:
	s_ashr_i32 s19, s18, 31
	v_lshl_or_b32 v208, s20, 8, v228
	s_lshl_b64 s[18:19], s[18:19], 8
	v_lshl_add_u64 v[216:217], s[18:19], 0, v[186:187]
	v_ashrrev_i32_e32 v209, 31, v208
	v_lshl_add_u64 v[18:19], v[208:209], 1, s[36:37]
	v_lshlrev_b64 v[214:215], 11, v[216:217]
	v_lshl_add_u64 v[18:19], v[18:19], 0, v[214:215]
	v_add_co_u32_e32 v20, vcc, 0x8000, v18
	s_mov_b32 s0, 0x10000
	s_nop 0
	v_addc_co_u32_e32 v21, vcc, 0, v19, vcc
	global_load_dwordx4 v[174:177], v[18:19], off
	global_load_dwordx4 v[170:173], v[18:19], off offset:256
	global_load_dwordx4 v[166:169], v[20:21], off
	global_load_dwordx4 v[162:165], v[20:21], off offset:256
	v_add_co_u32_e32 v20, vcc, s0, v18
	s_mov_b32 s0, 0x18000
	s_nop 0
	v_addc_co_u32_e32 v21, vcc, 0, v19, vcc
	v_add_co_u32_e32 v18, vcc, s0, v18
	v_lshl_add_u64 v[22:23], v[208:209], 2, s[42:43]
	s_nop 0
	v_addc_co_u32_e32 v19, vcc, 0, v19, vcc
	global_load_dwordx4 v[158:161], v[20:21], off
	global_load_dwordx4 v[154:157], v[20:21], off offset:256
	global_load_dwordx4 v[150:153], v[18:19], off
	global_load_dwordx4 v[138:141], v[18:19], off offset:256
	global_load_dwordx4 v[26:29], v[22:23], off offset:16
	global_load_dwordx4 v[30:33], v[22:23], off
	s_nop 0
	global_load_dwordx4 v[18:21], v[22:23], off offset:528
	s_nop 0
	global_load_dwordx4 v[22:25], v[22:23], off offset:512
	v_and_b32_e32 v211, 64, v249
	v_xor_b32_e32 v210, 16, v249
	v_add_u32_e32 v211, 64, v211
	v_cmp_lt_i32_e32 vcc, v210, v211
	v_mul_f32_e32 v212, v149, v149
	v_fmac_f32_e32 v212, v148, v148
	v_cndmask_b32_e32 v210, v249, v210, vcc
	v_lshlrev_b32_e32 v218, 2, v210
	v_mul_f32_e32 v210, v147, v147
	v_fmac_f32_e32 v210, v146, v146
	v_add_f32_e32 v210, v210, v212
	v_mul_f32_e32 v212, v143, v143
	v_mul_f32_e32 v213, v145, v145
	v_fmac_f32_e32 v212, v142, v142
	v_fmac_f32_e32 v213, v144, v144
	v_add_f32_e32 v212, v212, v213
	v_add_f32_e32 v210, v210, v212
	v_mul_f32_e32 v212, v135, v135
	v_mul_f32_e32 v213, v137, v137
	v_fmac_f32_e32 v212, v134, v134
	v_fmac_f32_e32 v213, v136, v136
	v_add_f32_e32 v212, v212, v213
	v_add_f32_e32 v210, v210, v212
	v_mul_f32_e32 v212, v131, v131
	v_mul_f32_e32 v213, v133, v133
	v_fmac_f32_e32 v212, v130, v130
	v_fmac_f32_e32 v213, v132, v132
	v_add_f32_e32 v212, v212, v213
	v_add_f32_e32 v210, v210, v212
	v_mov_b32_e32 v212, v210
	s_nop 1
	v_permlane16_swap_b32_e32 v212, v210
	v_xor_b32_e32 v213, 32, v249
	v_cmp_lt_i32_e32 vcc, v213, v211
	s_waitcnt lgkmcnt(0)
	v_add_f32_e32 v220, v210, v212
	v_cndmask_b32_e32 v211, v249, v213, vcc
	v_lshlrev_b32_e32 v219, 2, v211
	v_mov_b32_e32 v221, v220
	s_nop 1
	v_permlane32_swap_b32_e32 v221, v220
	s_and_saveexec_b64 s[0:1], s[10:11]
	s_cbranch_execz .LBB0_738
	s_waitcnt lgkmcnt(0)
	v_add_f32_e32 v210, v220, v221
	ds_write_b32 v229, v210
.LBB0_738:
	s_or_b64 exec, exec, s[0:1]
	v_mul_f32_e32 v210, v127, v127
	v_mul_f32_e32 v211, v129, v129
	v_fmac_f32_e32 v210, v126, v126
	v_fmac_f32_e32 v211, v128, v128
	v_add_f32_e32 v210, v210, v211
	v_mul_f32_e32 v211, v123, v123
	v_mul_f32_e32 v212, v125, v125
	v_fmac_f32_e32 v211, v122, v122
	v_fmac_f32_e32 v212, v124, v124
	v_add_f32_e32 v211, v211, v212
	v_add_f32_e32 v210, v210, v211
	v_mul_f32_e32 v211, v119, v119
	v_mul_f32_e32 v212, v121, v121
	v_fmac_f32_e32 v211, v118, v118
	v_fmac_f32_e32 v212, v120, v120
	v_add_f32_e32 v211, v211, v212
	v_add_f32_e32 v210, v210, v211
	v_mul_f32_e32 v211, v115, v115
	v_mul_f32_e32 v212, v117, v117
	v_fmac_f32_e32 v211, v114, v114
	v_fmac_f32_e32 v212, v116, v116
	v_add_f32_e32 v211, v211, v212
	v_add_f32_e32 v210, v210, v211
	v_mov_b32_e32 v211, v210
	s_nop 1
	v_permlane16_swap_b32_e32 v211, v210
	s_waitcnt lgkmcnt(0)
	v_add_f32_e32 v220, v210, v211
	v_mov_b32_e32 v221, v220
	s_nop 1
	v_permlane32_swap_b32_e32 v221, v220
	s_and_saveexec_b64 s[0:1], s[10:11]
	s_cbranch_execz .LBB0_740
	s_waitcnt lgkmcnt(0)
	v_add_f32_e32 v210, v220, v221
	ds_write_b32 v229, v210 offset:256
.LBB0_740:
	s_or_b64 exec, exec, s[0:1]
	v_mul_f32_e32 v210, v111, v111
	v_mul_f32_e32 v211, v113, v113
	v_fmac_f32_e32 v210, v110, v110
	v_fmac_f32_e32 v211, v112, v112
	v_add_f32_e32 v210, v210, v211
	v_mul_f32_e32 v211, v107, v107
	v_mul_f32_e32 v212, v109, v109
	v_fmac_f32_e32 v211, v106, v106
	v_fmac_f32_e32 v212, v108, v108
	v_add_f32_e32 v211, v211, v212
	v_add_f32_e32 v210, v210, v211
	v_mul_f32_e32 v211, v103, v103
	v_mul_f32_e32 v212, v105, v105
	v_fmac_f32_e32 v211, v102, v102
	v_fmac_f32_e32 v212, v104, v104
	v_add_f32_e32 v211, v211, v212
	v_add_f32_e32 v210, v210, v211
	v_mul_f32_e32 v211, v99, v99
	v_mul_f32_e32 v212, v101, v101
	v_fmac_f32_e32 v211, v98, v98
	v_fmac_f32_e32 v212, v100, v100
	v_add_f32_e32 v211, v211, v212
	v_add_f32_e32 v210, v210, v211
	v_mov_b32_e32 v211, v210
	s_nop 1
	v_permlane16_swap_b32_e32 v211, v210
	s_waitcnt lgkmcnt(0)
	v_add_f32_e32 v220, v210, v211
	v_mov_b32_e32 v221, v220
	s_nop 1
	v_permlane32_swap_b32_e32 v221, v220
	s_and_saveexec_b64 s[0:1], s[10:11]
	s_cbranch_execz .LBB0_742
	s_waitcnt lgkmcnt(0)
	v_add_f32_e32 v210, v220, v221
	ds_write_b32 v229, v210 offset:512
;     __device__ __forceinline__ void operator()(const f32x4 (&acc)[2][2][4][2], const pg8::Unit& u, int wr, int wc, int fr, int fq, LAS unsigned char* lds, int wid, int lane, const pg8::Unit& nxt, bool has_next, int ui) const {
;     ...
;         for (int ai = 0; ai < 2; ++ai)
; #pragma unroll
;             for (int m = 0; m < 4; ++m) { float ss = 0.f;
; #pragma unroll
;                 for (int bj = 0; bj < 2; ++bj)
; #pragma unroll
;                     for (int n = 0; n < 2; ++n) { const f32x4 v = acc[ai][bj][m][n]; ss += (v[0] * v[0] + v[1] * v[1]) + (v[2] * v[2] + v[3] * v[3]); }
;                 ss += __shfl_xor(ss, 16); ss += __shfl_xor(ss, 32);
;                 if (fq == 0) P[(rl0 + ai * 128 + m * 16) * 4 + wc] = ss; }
.LBB0_742:
	s_or_b64 exec, exec, s[0:1]
	v_mul_f32_e32 v210, v95, v95
	v_mul_f32_e32 v211, v97, v97
	v_fmac_f32_e32 v210, v94, v94
	v_fmac_f32_e32 v211, v96, v96
	v_add_f32_e32 v210, v210, v211
	v_mul_f32_e32 v211, v91, v91
	v_mul_f32_e32 v212, v93, v93
	v_fmac_f32_e32 v211, v90, v90
	v_fmac_f32_e32 v212, v92, v92
	v_add_f32_e32 v211, v211, v212
	v_add_f32_e32 v210, v210, v211
	v_mul_f32_e32 v211, v87, v87
	v_mul_f32_e32 v212, v89, v89
	v_fmac_f32_e32 v211, v86, v86
	v_fmac_f32_e32 v212, v88, v88
	v_add_f32_e32 v211, v211, v212
	v_add_f32_e32 v210, v210, v211
	v_mul_f32_e32 v211, v83, v83
	v_mul_f32_e32 v212, v85, v85
	v_fmac_f32_e32 v211, v82, v82
	v_fmac_f32_e32 v212, v84, v84
	v_add_f32_e32 v211, v211, v212
	v_add_f32_e32 v210, v210, v211
	v_mov_b32_e32 v211, v210
	s_nop 1
	v_permlane16_swap_b32_e32 v211, v210
	s_waitcnt lgkmcnt(0)
	v_add_f32_e32 v220, v210, v211
	v_mov_b32_e32 v221, v220
	s_nop 1
	v_permlane32_swap_b32_e32 v221, v220
	s_and_saveexec_b64 s[0:1], s[10:11]
	s_cbranch_execz .LBB0_744
	s_waitcnt lgkmcnt(0)
	v_add_f32_e32 v210, v220, v221
	ds_write_b32 v229, v210 offset:768
.LBB0_744:
	s_or_b64 exec, exec, s[0:1]
	v_mul_f32_e32 v210, v79, v79
	v_mul_f32_e32 v211, v81, v81
	v_fmac_f32_e32 v210, v78, v78
	v_fmac_f32_e32 v211, v80, v80
	v_add_f32_e32 v210, v210, v211
	v_mul_f32_e32 v211, v75, v75
	v_mul_f32_e32 v212, v77, v77
	v_fmac_f32_e32 v211, v74, v74
	v_fmac_f32_e32 v212, v76, v76
	v_add_f32_e32 v211, v211, v212
	v_add_f32_e32 v210, v210, v211
	v_mul_f32_e32 v211, v71, v71
	v_mul_f32_e32 v212, v73, v73
	v_fmac_f32_e32 v211, v70, v70
	v_fmac_f32_e32 v212, v72, v72
	v_add_f32_e32 v211, v211, v212
	v_add_f32_e32 v210, v210, v211
	v_mul_f32_e32 v211, v67, v67
	v_mul_f32_e32 v212, v69, v69
	v_fmac_f32_e32 v211, v66, v66
	v_fmac_f32_e32 v212, v68, v68
	v_add_f32_e32 v211, v211, v212
	v_add_f32_e32 v210, v210, v211
	v_mov_b32_e32 v211, v210
	s_nop 1
	v_permlane16_swap_b32_e32 v211, v210
	s_waitcnt lgkmcnt(0)
	v_add_f32_e32 v220, v210, v211
	v_mov_b32_e32 v221, v220
	s_nop 1
	v_permlane32_swap_b32_e32 v221, v220
	s_and_saveexec_b64 s[0:1], s[10:11]
	s_cbranch_execz .LBB0_746
	s_waitcnt lgkmcnt(0)
	v_add_f32_e32 v210, v220, v221
	ds_write_b32 v229, v210 offset:2048
.LBB0_746:
	s_or_b64 exec, exec, s[0:1]
	v_mul_f32_e32 v210, v63, v63
	v_mul_f32_e32 v211, v65, v65
	v_fmac_f32_e32 v210, v62, v62
	v_fmac_f32_e32 v211, v64, v64
	v_add_f32_e32 v210, v210, v211
	v_mul_f32_e32 v211, v59, v59
	v_mul_f32_e32 v212, v61, v61
	v_fmac_f32_e32 v211, v58, v58
	v_fmac_f32_e32 v212, v60, v60
	v_add_f32_e32 v211, v211, v212
	v_add_f32_e32 v210, v210, v211
	v_mul_f32_e32 v211, v55, v55
	v_mul_f32_e32 v212, v57, v57
	v_fmac_f32_e32 v211, v54, v54
	v_fmac_f32_e32 v212, v56, v56
	v_add_f32_e32 v211, v211, v212
	v_add_f32_e32 v210, v210, v211
	v_mul_f32_e32 v211, v51, v51
	v_mul_f32_e32 v212, v53, v53
	v_fmac_f32_e32 v211, v50, v50
	v_fmac_f32_e32 v212, v52, v52
	v_add_f32_e32 v211, v211, v212
	v_add_f32_e32 v210, v210, v211
	v_mov_b32_e32 v211, v210
	s_nop 1
	v_permlane16_swap_b32_e32 v211, v210
	s_waitcnt lgkmcnt(0)
	v_add_f32_e32 v220, v210, v211
	v_mov_b32_e32 v221, v220
	s_nop 1
	v_permlane32_swap_b32_e32 v221, v220
	s_and_saveexec_b64 s[0:1], s[10:11]
	s_cbranch_execz .LBB0_748
	s_waitcnt lgkmcnt(0)
	v_add_f32_e32 v210, v220, v221
	ds_write_b32 v229, v210 offset:2304
.LBB0_748:
	s_or_b64 exec, exec, s[0:1]
	v_mul_f32_e32 v210, v47, v47
	v_mul_f32_e32 v211, v49, v49
	v_fmac_f32_e32 v210, v46, v46
	v_fmac_f32_e32 v211, v48, v48
	v_add_f32_e32 v210, v210, v211
	v_mul_f32_e32 v211, v43, v43
	v_mul_f32_e32 v212, v45, v45
	v_fmac_f32_e32 v211, v42, v42
	v_fmac_f32_e32 v212, v44, v44
	v_add_f32_e32 v211, v211, v212
	v_add_f32_e32 v210, v210, v211
	v_mul_f32_e32 v211, v39, v39
	v_mul_f32_e32 v212, v41, v41
	v_fmac_f32_e32 v211, v38, v38
	v_fmac_f32_e32 v212, v40, v40
	v_add_f32_e32 v211, v211, v212
	v_add_f32_e32 v210, v210, v211
	v_mul_f32_e32 v211, v35, v35
	v_mul_f32_e32 v212, v37, v37
	v_fmac_f32_e32 v211, v34, v34
	v_fmac_f32_e32 v212, v36, v36
	v_add_f32_e32 v211, v211, v212
	v_add_f32_e32 v210, v210, v211
	v_mov_b32_e32 v211, v210
	s_nop 1
	v_permlane16_swap_b32_e32 v211, v210
	s_waitcnt lgkmcnt(0)
	v_add_f32_e32 v220, v210, v211
	v_mov_b32_e32 v221, v220
	s_nop 1
	v_permlane32_swap_b32_e32 v221, v220
	s_and_saveexec_b64 s[0:1], s[10:11]
	s_cbranch_execz .LBB0_750
	s_waitcnt lgkmcnt(0)
	v_add_f32_e32 v210, v220, v221
	ds_write_b32 v229, v210 offset:2560
.LBB0_750:
	s_or_b64 exec, exec, s[0:1]
	v_mul_f32_e32 v210, v15, v15
	v_mul_f32_e32 v211, v17, v17
	v_fmac_f32_e32 v210, v14, v14
	v_fmac_f32_e32 v211, v16, v16
	v_add_f32_e32 v210, v210, v211
	v_mul_f32_e32 v211, v11, v11
	v_mul_f32_e32 v212, v13, v13
	v_fmac_f32_e32 v211, v10, v10
	v_fmac_f32_e32 v212, v12, v12
	v_add_f32_e32 v211, v211, v212
	v_add_f32_e32 v210, v210, v211
	v_mul_f32_e32 v211, v7, v7
	v_mul_f32_e32 v212, v9, v9
	v_fmac_f32_e32 v211, v6, v6
	v_fmac_f32_e32 v212, v8, v8
	v_add_f32_e32 v211, v211, v212
	v_add_f32_e32 v210, v210, v211
	v_mul_f32_e32 v211, v3, v3
	v_mul_f32_e32 v212, v5, v5
	v_fmac_f32_e32 v211, v2, v2
	v_fmac_f32_e32 v212, v4, v4
	v_add_f32_e32 v211, v211, v212
	v_add_f32_e32 v210, v210, v211
	v_mov_b32_e32 v211, v210
	s_nop 1
	v_permlane16_swap_b32_e32 v211, v210
	s_waitcnt lgkmcnt(0)
	v_add_f32_e32 v218, v210, v211
	v_mov_b32_e32 v219, v218
	s_nop 1
	v_permlane32_swap_b32_e32 v219, v218
	s_and_saveexec_b64 s[0:1], s[10:11]
	s_cbranch_execz .LBB0_752
	s_waitcnt lgkmcnt(0)
	v_add_f32_e32 v210, v218, v219
	ds_write_b32 v229, v210 offset:2816
